# gate/groupnorm loop: norm weights hoisted out of row loop; rms/final-norm sample rows: weight loads issued up front; GLU epilogue bias hoisted + waits recomputed
# speedup vs baseline: 1.0267x; 1.0085x over previous
.LBB0_564:
	global_load_dwordx4 v[100:103], v[20:21], off
	global_load_dwordx4 v[104:107], v[20:21], off offset:1024
	global_load_dwordx4 v[108:111], v[20:21], off offset:2048
	global_load_dwordx4 v[112:115], v[20:21], off offset:3072
	v_lshl_add_u64 v[0:1], s[0:1], 0, v[18:19]
	v_add_co_u32_e32 v22, vcc, 0x4000000, v0
	s_mov_b32 s6, 0x14914000
	s_nop 0
	v_addc_co_u32_e32 v23, vcc, 0, v1, vcc
	v_lshl_add_u64 v[0:1], s[4:5], 0, v[18:19]
	v_add_co_u32_e32 v14, vcc, 0x14114000, v0
	global_load_dwordx4 v[2:5], v[22:23], off
	global_load_dwordx4 v[6:9], v[22:23], off offset:1024
	global_load_dwordx4 v[10:13], v[22:23], off offset:2048
	global_load_dwordx4 v[32:35], v[22:23], off offset:3072
	v_addc_co_u32_e32 v15, vcc, 0, v1, vcc
	global_load_dwordx4 v[36:39], v[14:15], off
	global_load_dwordx4 v[40:43], v[14:15], off offset:1024
	global_load_dwordx4 v[44:47], v[14:15], off offset:2048
	global_load_dwordx4 v[48:51], v[14:15], off offset:3072
	v_add_co_u32_e32 v14, vcc, 0x14314000, v0
	s_waitcnt vmcnt(0)
	v_pk_add_f32 v[4:5], v[4:5], v[38:39]
	v_addc_co_u32_e32 v15, vcc, 0, v1, vcc
	global_load_dwordx4 v[52:55], v[14:15], off
	global_load_dwordx4 v[56:59], v[14:15], off offset:1024
	global_load_dwordx4 v[60:63], v[14:15], off offset:2048
	global_load_dwordx4 v[64:67], v[14:15], off offset:3072
	v_add_co_u32_e32 v14, vcc, 0x14514000, v0
	v_pk_add_f32 v[32:33], v[32:33], v[48:49]
	s_nop 0
	v_addc_co_u32_e32 v15, vcc, 0, v1, vcc
	global_load_dwordx4 v[68:71], v[14:15], off
	global_load_dwordx4 v[72:75], v[14:15], off offset:1024
	global_load_dwordx4 v[76:79], v[14:15], off offset:2048
	global_load_dwordx4 v[80:83], v[14:15], off offset:3072
	v_add_co_u32_e32 v14, vcc, 0x14714000, v0
	v_pk_add_f32 v[2:3], v[2:3], v[36:37]
	s_nop 0
	v_addc_co_u32_e32 v15, vcc, 0, v1, vcc
	global_load_dwordx4 v[84:87], v[14:15], off
	global_load_dwordx4 v[88:91], v[14:15], off offset:1024
	global_load_dwordx4 v[92:95], v[14:15], off offset:2048
	global_load_dwordx4 v[96:99], v[14:15], off offset:3072
	v_pk_add_f32 v[8:9], v[8:9], v[42:43]
	v_pk_add_f32 v[6:7], v[6:7], v[40:41]
	v_pk_add_f32 v[12:13], v[12:13], v[46:47]
	v_pk_add_f32 v[10:11], v[10:11], v[44:45]
	v_pk_add_f32 v[14:15], v[34:35], v[50:51]
	s_waitcnt vmcnt(11)
	v_pk_add_f32 v[4:5], v[4:5], v[54:55]
	v_pk_add_f32 v[2:3], v[2:3], v[52:53]
	s_waitcnt vmcnt(10)
	v_pk_add_f32 v[8:9], v[8:9], v[58:59]
	s_waitcnt vmcnt(8)
	v_pk_add_f32 v[32:33], v[32:33], v[64:65]
	v_pk_add_f32 v[6:7], v[6:7], v[56:57]
	v_pk_add_f32 v[12:13], v[12:13], v[62:63]
	v_pk_add_f32 v[10:11], v[10:11], v[60:61]
	s_waitcnt vmcnt(7)
	v_pk_add_f32 v[4:5], v[4:5], v[70:71]
	v_pk_add_f32 v[2:3], v[2:3], v[68:69]
	s_waitcnt vmcnt(4)
	v_pk_add_f32 v[32:33], v[32:33], v[80:81]
	v_pk_add_f32 v[8:9], v[8:9], v[74:75]
	v_pk_add_f32 v[6:7], v[6:7], v[72:73]
	v_pk_add_f32 v[12:13], v[12:13], v[78:79]
	v_pk_add_f32 v[10:11], v[10:11], v[76:77]
	s_waitcnt vmcnt(3)
	v_pk_add_f32 v[86:87], v[4:5], v[86:87]
	s_waitcnt vmcnt(0)
	v_pk_add_f32 v[96:97], v[32:33], v[96:97]
	v_add_co_u32_e32 v32, vcc, s6, v0
	s_mov_b32 s6, 0x14b14000
	s_nop 0
	v_addc_co_u32_e32 v33, vcc, 0, v1, vcc
	v_add_co_u32_e32 v48, vcc, s6, v0
	s_mov_b32 s6, 0x14d14000
	s_nop 0
	v_addc_co_u32_e32 v49, vcc, 0, v1, vcc
	v_add_co_u32_e32 v64, vcc, s6, v0
	v_pk_add_f32 v[84:85], v[2:3], v[84:85]
	v_pk_add_f32 v[90:91], v[8:9], v[90:91]
	v_pk_add_f32 v[88:89], v[6:7], v[88:89]
	v_pk_add_f32 v[94:95], v[12:13], v[94:95]
	v_pk_add_f32 v[92:93], v[10:11], v[92:93]
	global_load_dwordx4 v[2:5], v[32:33], off
	global_load_dwordx4 v[6:9], v[32:33], off offset:1024
	global_load_dwordx4 v[10:13], v[32:33], off offset:2048
	s_nop 0
	global_load_dwordx4 v[32:35], v[32:33], off offset:3072
	v_addc_co_u32_e32 v65, vcc, 0, v1, vcc
	s_mov_b32 s6, 0x14f14000
	global_load_dwordx4 v[36:39], v[48:49], off
	global_load_dwordx4 v[40:43], v[48:49], off offset:1024
	global_load_dwordx4 v[44:47], v[48:49], off offset:2048
	s_nop 0
	global_load_dwordx4 v[48:51], v[48:49], off offset:3072
	v_add_co_u32_e32 v80, vcc, s6, v0
	v_pk_add_f32 v[14:15], v[14:15], v[66:67]
	global_load_dwordx4 v[52:55], v[64:65], off
	global_load_dwordx4 v[56:59], v[64:65], off offset:1024
	global_load_dwordx4 v[60:63], v[64:65], off offset:2048
	s_nop 0
	global_load_dwordx4 v[64:67], v[64:65], off offset:3072
	v_addc_co_u32_e32 v81, vcc, 0, v1, vcc
	v_pk_add_f32 v[14:15], v[14:15], v[82:83]
	global_load_dwordx4 v[68:71], v[80:81], off
	global_load_dwordx4 v[72:75], v[80:81], off offset:1024
	global_load_dwordx4 v[76:79], v[80:81], off offset:2048
	s_nop 0
	global_load_dwordx4 v[80:83], v[80:81], off offset:3072
	s_mov_b32 s6, 0x15114000
	v_pk_add_f32 v[14:15], v[14:15], v[98:99]
	s_waitcnt vmcnt(15)
	v_pk_add_f32 v[4:5], v[86:87], v[4:5]
	v_pk_add_f32 v[2:3], v[84:85], v[2:3]
	s_waitcnt vmcnt(14)
	v_pk_add_f32 v[8:9], v[90:91], v[8:9]
	s_waitcnt vmcnt(12)
	v_pk_add_f32 v[32:33], v[96:97], v[32:33]
	v_pk_add_f32 v[6:7], v[88:89], v[6:7]
	v_pk_add_f32 v[12:13], v[94:95], v[12:13]
	v_pk_add_f32 v[10:11], v[92:93], v[10:11]
	s_waitcnt vmcnt(8)
	v_pk_add_f32 v[32:33], v[32:33], v[48:49]
	v_pk_add_f32 v[4:5], v[4:5], v[38:39]
	v_pk_add_f32 v[2:3], v[2:3], v[36:37]
	v_pk_add_f32 v[8:9], v[8:9], v[42:43]
	s_waitcnt vmcnt(4)
	v_pk_add_f32 v[32:33], v[32:33], v[64:65]
	v_pk_add_f32 v[6:7], v[6:7], v[40:41]
	v_pk_add_f32 v[12:13], v[12:13], v[46:47]
	v_pk_add_f32 v[10:11], v[10:11], v[44:45]
	s_waitcnt vmcnt(0)
	v_pk_add_f32 v[80:81], v[32:33], v[80:81]
	v_add_co_u32_e32 v32, vcc, s6, v0
	s_mov_b32 s6, 0x15314000
	s_nop 0
	v_addc_co_u32_e32 v33, vcc, 0, v1, vcc
	v_add_co_u32_e32 v48, vcc, s6, v0
	v_pk_add_f32 v[4:5], v[4:5], v[54:55]
	v_pk_add_f32 v[2:3], v[2:3], v[52:53]
	v_pk_add_f32 v[8:9], v[8:9], v[58:59]
	v_pk_add_f32 v[6:7], v[6:7], v[56:57]
	v_pk_add_f32 v[12:13], v[12:13], v[62:63]
	v_pk_add_f32 v[10:11], v[10:11], v[60:61]
	v_addc_co_u32_e32 v49, vcc, 0, v1, vcc
	s_mov_b32 s6, 0x15514000
	v_pk_add_f32 v[14:15], v[14:15], v[34:35]
	v_pk_add_f32 v[70:71], v[4:5], v[70:71]
	v_pk_add_f32 v[68:69], v[2:3], v[68:69]
	v_pk_add_f32 v[74:75], v[8:9], v[74:75]
	v_pk_add_f32 v[72:73], v[6:7], v[72:73]
	v_pk_add_f32 v[78:79], v[12:13], v[78:79]
	v_pk_add_f32 v[76:77], v[10:11], v[76:77]
	global_load_dwordx4 v[2:5], v[32:33], off
	global_load_dwordx4 v[6:9], v[32:33], off offset:1024
	global_load_dwordx4 v[10:13], v[32:33], off offset:2048
	s_nop 0
	global_load_dwordx4 v[32:35], v[32:33], off offset:3072
	v_add_co_u32_e32 v0, vcc, s6, v0
	v_pk_add_f32 v[14:15], v[14:15], v[50:51]
	global_load_dwordx4 v[36:39], v[48:49], off
	global_load_dwordx4 v[40:43], v[48:49], off offset:1024
	global_load_dwordx4 v[44:47], v[48:49], off offset:2048
	s_nop 0
	global_load_dwordx4 v[48:51], v[48:49], off offset:3072
	v_addc_co_u32_e32 v1, vcc, 0, v1, vcc
	v_pk_add_f32 v[14:15], v[14:15], v[66:67]
	global_load_dwordx4 v[52:55], v[0:1], off
	global_load_dwordx4 v[56:59], v[0:1], off offset:1024
	global_load_dwordx4 v[60:63], v[0:1], off offset:2048
	global_load_dwordx4 v[64:67], v[0:1], off offset:3072
	v_pk_add_f32 v[14:15], v[14:15], v[82:83]
	s_mov_b32 s6, 0x800000
	s_waitcnt vmcnt(11)
	v_pk_add_f32 v[0:1], v[70:71], v[4:5]
	v_pk_add_f32 v[2:3], v[68:69], v[2:3]
	s_waitcnt vmcnt(10)
	v_pk_add_f32 v[4:5], v[74:75], v[8:9]
	v_pk_add_f32 v[6:7], v[72:73], v[6:7]
	s_waitcnt vmcnt(9)
	v_pk_add_f32 v[8:9], v[78:79], v[12:13]
	v_pk_add_f32 v[10:11], v[76:77], v[10:11]
	s_waitcnt vmcnt(8)
	v_pk_add_f32 v[12:13], v[14:15], v[34:35]
	v_pk_add_f32 v[14:15], v[80:81], v[32:33]
	s_waitcnt vmcnt(7)
	v_pk_add_f32 v[0:1], v[0:1], v[38:39]
	v_pk_add_f32 v[2:3], v[2:3], v[36:37]
	s_waitcnt vmcnt(6)
	v_pk_add_f32 v[4:5], v[4:5], v[42:43]
	v_pk_add_f32 v[6:7], v[6:7], v[40:41]
	s_waitcnt vmcnt(5)
	v_pk_add_f32 v[8:9], v[8:9], v[46:47]
	v_pk_add_f32 v[10:11], v[10:11], v[44:45]
	s_waitcnt vmcnt(4)
	v_pk_add_f32 v[12:13], v[12:13], v[50:51]
	v_pk_add_f32 v[14:15], v[14:15], v[48:49]
	s_waitcnt vmcnt(3)
	v_pk_add_f32 v[0:1], v[0:1], v[54:55]
	v_pk_add_f32 v[2:3], v[2:3], v[52:53]
	s_waitcnt vmcnt(2)
	v_pk_add_f32 v[4:5], v[4:5], v[58:59]
	v_pk_add_f32 v[6:7], v[6:7], v[56:57]
	s_waitcnt vmcnt(1)
	v_pk_add_f32 v[32:33], v[8:9], v[62:63]
	v_pk_add_f32 v[34:35], v[10:11], v[60:61]
	s_waitcnt vmcnt(0)
	v_pk_add_f32 v[36:37], v[12:13], v[66:67]
	v_pk_add_f32 v[38:39], v[14:15], v[64:65]
	v_pk_fma_f32 v[14:15], v[54:55], 0, v[0:1] op_sel_hi:[1,0,1]
	v_pk_fma_f32 v[12:13], v[52:53], 0, v[2:3] op_sel_hi:[1,0,1]
	v_pk_fma_f32 v[10:11], v[58:59], 0, v[4:5] op_sel_hi:[1,0,1]
	v_pk_fma_f32 v[8:9], v[56:57], 0, v[6:7] op_sel_hi:[1,0,1]
	v_pk_fma_f32 v[6:7], v[62:63], 0, v[32:33] op_sel_hi:[1,0,1]
	v_pk_fma_f32 v[4:5], v[60:61], 0, v[34:35] op_sel_hi:[1,0,1]
	v_pk_mul_f32 v[32:33], v[14:15], v[14:15]
	v_pk_mul_f32 v[34:35], v[12:13], v[12:13]
	v_pk_fma_f32 v[2:3], v[66:67], 0, v[36:37] op_sel_hi:[1,0,1]
	v_pk_mov_b32 v[36:37], v[34:35], v[32:33] op_sel:[1,0]
	v_mov_b32_e32 v35, v33
	v_pk_add_f32 v[32:33], v[36:37], v[34:35]
	v_pk_mul_f32 v[34:35], v[10:11], v[10:11]
	v_pk_mul_f32 v[36:37], v[8:9], v[8:9]
	v_pk_fma_f32 v[0:1], v[64:65], 0, v[38:39] op_sel_hi:[1,0,1]
	v_pk_mov_b32 v[38:39], v[36:37], v[34:35] op_sel:[1,0]
	v_mov_b32_e32 v37, v35
	v_pk_add_f32 v[34:35], v[38:39], v[36:37]
	global_store_dwordx4 v[22:23], v[12:15], off
	global_store_dwordx4 v[22:23], v[8:11], off offset:1024
	global_store_dwordx4 v[22:23], v[4:7], off offset:2048
	global_store_dwordx4 v[22:23], v[0:3], off offset:3072
	v_mul_f32_e32 v31, v0, v0
	v_mul_f32_e32 v36, v1, v1
	v_pk_add_f32 v[22:23], v[32:33], v[32:33] op_sel:[0,1] op_sel_hi:[1,0]
	v_pk_add_f32 v[32:33], v[34:35], v[34:35] op_sel:[0,1] op_sel_hi:[1,0]
	v_mov_b32_e32 v23, v31
	v_mov_b32_e32 v33, v36
	v_pk_add_f32 v[22:23], v[22:23], v[32:33]
	v_mul_f32_e32 v32, v5, v5
	v_mul_f32_e32 v34, v7, v7
	v_mul_f32_e32 v37, v2, v2
	v_mul_f32_e32 v38, v3, v3
	v_pk_fma_f32 v[32:33], v[4:5], v[4:5], v[32:33] op_sel_hi:[1,1,0]
	v_pk_fma_f32 v[34:35], v[6:7], v[6:7], v[34:35] op_sel_hi:[1,1,0]
	v_mov_b32_e32 v33, v37
	v_mov_b32_e32 v35, v38
	v_pk_add_f32 v[32:33], v[32:33], v[34:35]
	s_nop 0
	v_pk_add_f32 v[22:23], v[22:23], v[32:33]
	v_add_f32_e32 v22, v22, v23
	ds_bpermute_b32 v23, v24, v22
	s_waitcnt lgkmcnt(0)
	v_add_f32_e32 v22, v22, v23
	ds_bpermute_b32 v23, v25, v22
	s_waitcnt lgkmcnt(0)
	v_add_f32_e32 v22, v22, v23
	ds_bpermute_b32 v23, v26, v22
	s_waitcnt lgkmcnt(0)
	v_add_f32_e32 v22, v22, v23
	ds_bpermute_b32 v23, v27, v22
	s_waitcnt lgkmcnt(0)
	v_add_f32_e32 v22, v22, v23
	ds_bpermute_b32 v23, v28, v22
	s_waitcnt lgkmcnt(0)
	v_add_f32_e32 v22, v22, v23
	ds_bpermute_b32 v23, v29, v22
	s_waitcnt lgkmcnt(0)
	v_add_f32_e32 v22, v22, v23
	v_fmamk_f32 v22, v22, 0x3a800000, v30
	v_cmp_gt_f32_e32 vcc, s6, v22
	v_mul_f32_e32 v23, 0x4b800000, v22
	s_add_i32 s6, s8, 0x4000
	v_cndmask_b32_e32 v22, v22, v23, vcc
	v_rsq_f32_e32 v22, v22
	s_ashr_i32 s7, s6, 31
	s_lshl_b64 s[6:7], s[6:7], 11
	s_add_i32 s8, s8, s56
	v_mul_f32_e32 v23, 0x45800000, v22
	v_cndmask_b32_e32 v31, v22, v23, vcc
	v_mul_f32_e32 v12, v12, v31
	v_mul_f32_e32 v13, v13, v31
	v_lshl_add_u64 v[22:23], v[16:17], 0, s[6:7]
	v_mul_f32_e32 v8, v8, v31
	v_mul_f32_e32 v9, v9, v31
	v_mul_f32_e32 v4, v4, v31
	v_mul_f32_e32 v5, v5, v31
	s_add_u32 s0, s0, s2
	v_mul_f32_e32 v0, v0, v31
	v_mul_f32_e32 v1, v1, v31
	s_addc_u32 s1, s1, s3
	s_add_u32 s4, s4, s2
	s_addc_u32 s5, s5, s3
	s_cmpk_lt_i32 s8, 0x200
	v_mul_f32_e32 v12, v100, v12
	v_mul_f32_e32 v13, v101, v13
	v_cvt_pk_bf16_f32 v12, v12, v13
	v_mul_f32_e32 v13, v14, v31
	v_mul_f32_e32 v13, v102, v13
	v_mul_f32_e32 v14, v15, v31
	v_mul_f32_e32 v14, v103, v14
	v_cvt_pk_bf16_f32 v13, v13, v14
	global_store_dwordx2 v[22:23], v[12:13], off
	v_mul_f32_e32 v8, v104, v8
	v_mul_f32_e32 v9, v105, v9
	v_cvt_pk_bf16_f32 v8, v8, v9
	v_mul_f32_e32 v9, v10, v31
	v_mul_f32_e32 v9, v106, v9
	v_mul_f32_e32 v10, v11, v31
	v_mul_f32_e32 v10, v107, v10
	v_cvt_pk_bf16_f32 v9, v9, v10
	global_store_dwordx2 v[22:23], v[8:9], off offset:512
	v_mul_f32_e32 v4, v4, v108
	v_mul_f32_e32 v5, v5, v109
	v_cvt_pk_bf16_f32 v4, v4, v5
	v_mul_f32_e32 v5, v6, v31
	v_mul_f32_e32 v5, v5, v110
	v_mul_f32_e32 v6, v7, v31
	v_mul_f32_e32 v6, v6, v111
	v_cvt_pk_bf16_f32 v5, v5, v6
	global_store_dwordx2 v[22:23], v[4:5], off offset:1024
	v_mul_f32_e32 v0, v0, v112
	v_mul_f32_e32 v1, v1, v113
	v_cvt_pk_bf16_f32 v0, v0, v1
	v_mul_f32_e32 v1, v2, v31
	v_mul_f32_e32 v1, v1, v114
	v_mul_f32_e32 v2, v3, v31
	v_mul_f32_e32 v2, v2, v115
	v_cvt_pk_bf16_f32 v1, v1, v2
	global_store_dwordx2 v[22:23], v[0:1], off offset:1536
	s_cbranch_scc1 .LBB0_564

.LBB0_1339:
	v_lshl_or_b32 v142, s38, 8, v152
	v_readlane_b32 s56, v252, 32
	v_ashrrev_i32_e32 v143, 31, v142
	v_readlane_b32 s66, v252, 42
	v_readlane_b32 s67, v252, 43
	v_lshl_add_u32 v144, s37, 8, v150
	v_ashrrev_i32_e32 v145, 31, v144
	v_lshl_add_u64 v[140:141], v[142:143], 2, s[66:67]
	global_load_dwordx4 v[232:235], v[140:141], off
	global_load_dwordx4 v[236:239], v[140:141], off offset:64
	global_load_dwordx4 v[240:243], v[140:141], off offset:512
	global_load_dwordx4 v[244:247], v[140:141], off offset:576
	v_lshlrev_b64 v[146:147], 10, v[144:145]
	v_lshlrev_b64 v[142:143], 1, v[142:143]
	v_lshl_add_u64 v[146:147], s[82:83], 0, v[146:147]
	v_lshl_add_u64 v[148:149], v[146:147], 0, v[142:143]
	global_load_dwordx2 v[160:161], v[148:149], off
	global_load_dwordx2 v[162:163], v[148:149], off offset:32
	v_readlane_b32 s18, v251, 47
	v_lshlrev_b64 v[146:147], 12, v[144:145]
	v_readlane_b32 s19, v251, 48
	s_and_b64 vcc, exec, s[6:7]
	s_mov_b64 s[6:7], -1
	v_lshl_add_u64 v[146:147], s[18:19], 0, v[146:147]
	v_lshl_add_u64 v[146:147], v[146:147], 0, v[142:143]
	v_readlane_b32 s57, v252, 33
	v_readlane_b32 s58, v252, 34
	v_readlane_b32 s59, v252, 35
	v_readlane_b32 s60, v252, 36
	v_readlane_b32 s61, v252, 37
	v_readlane_b32 s62, v252, 38
	v_readlane_b32 s63, v252, 39
	v_readlane_b32 s64, v252, 40
	v_readlane_b32 s65, v252, 41
	v_readlane_b32 s68, v252, 44
	v_readlane_b32 s69, v252, 45
	v_readlane_b32 s70, v252, 46
	v_readlane_b32 s71, v252, 47
	s_waitcnt vmcnt(0)
	v_add_f32_e32 v124, v124, v232
	v_add_f32_e32 v125, v125, v233
	v_add_f32_e32 v126, v126, v234
	v_add_f32_e32 v127, v127, v235
	v_mul_f32_e32 v124, 0xbfb8aa3b, v124
	v_mul_f32_e32 v125, 0xbfb8aa3b, v125
	v_mul_f32_e32 v126, 0xbfb8aa3b, v126
	v_mul_f32_e32 v127, 0xbfb8aa3b, v127
	v_exp_f32_e32 v124, v124
	v_exp_f32_e32 v125, v125
	v_exp_f32_e32 v126, v126
	v_exp_f32_e32 v127, v127
	v_add_f32_e32 v124, 1.0, v124
	v_add_f32_e32 v125, 1.0, v125
	v_add_f32_e32 v126, 1.0, v126
	v_add_f32_e32 v127, 1.0, v127
	v_rcp_f32_e32 v124, v124
	v_rcp_f32_e32 v125, v125
	v_rcp_f32_e32 v126, v126
	v_rcp_f32_e32 v127, v127
	v_lshlrev_b32_e32 v145, 16, v160
	v_and_b32_e32 v156, 0xffff0000, v160
	v_lshlrev_b32_e32 v157, 16, v161
	v_and_b32_e32 v158, 0xffff0000, v161
	v_mul_f32_e32 v124, v124, v145
	v_mul_f32_e32 v125, v125, v156
	v_mul_f32_e32 v126, v126, v157
	v_mul_f32_e32 v127, v127, v158
	v_cvt_pk_bf16_f32 v124, v124, v125
	v_cvt_pk_bf16_f32 v125, v126, v127
	global_store_dwordx2 v[146:147], v[124:125], off
	s_nop 0
	global_load_dwordx2 v[156:157], v[148:149], off offset:256
	v_lshlrev_b32_e32 v145, 16, v162
	v_and_b32_e32 v158, 0xffff0000, v162
	v_lshlrev_b32_e32 v159, 16, v163
	v_and_b32_e32 v160, 0xffff0000, v163
	v_add_f32_e32 v120, v120, v236
	v_add_f32_e32 v121, v121, v237
	v_add_f32_e32 v122, v122, v238
	v_add_f32_e32 v123, v123, v239
	v_mul_f32_e32 v120, 0xbfb8aa3b, v120
	v_mul_f32_e32 v121, 0xbfb8aa3b, v121
	v_mul_f32_e32 v122, 0xbfb8aa3b, v122
	v_mul_f32_e32 v123, 0xbfb8aa3b, v123
	v_exp_f32_e32 v120, v120
	v_exp_f32_e32 v121, v121
	v_exp_f32_e32 v122, v122
	v_exp_f32_e32 v123, v123
	v_add_f32_e32 v120, 1.0, v120
	v_add_f32_e32 v121, 1.0, v121
	v_add_f32_e32 v122, 1.0, v122
	v_add_f32_e32 v123, 1.0, v123
	v_rcp_f32_e32 v120, v120
	v_rcp_f32_e32 v121, v121
	v_rcp_f32_e32 v122, v122
	v_rcp_f32_e32 v123, v123
	v_mul_f32_e32 v120, v120, v145
	v_mul_f32_e32 v121, v121, v158
	v_mul_f32_e32 v122, v122, v159
	v_mul_f32_e32 v123, v123, v160
	v_cvt_pk_bf16_f32 v120, v120, v121
	v_cvt_pk_bf16_f32 v121, v122, v123
	global_store_dwordx2 v[146:147], v[120:121], off offset:32
	s_nop 0
	global_load_dwordx2 v[120:121], v[148:149], off offset:288
	s_waitcnt vmcnt(2)
	v_lshlrev_b32_e32 v126, 16, v156
	v_and_b32_e32 v127, 0xffff0000, v156
	v_lshlrev_b32_e32 v145, 16, v157
	v_and_b32_e32 v148, 0xffff0000, v157
	v_add_f32_e32 v116, v116, v240
	v_add_f32_e32 v117, v117, v241
	v_add_f32_e32 v118, v118, v242
	v_add_f32_e32 v119, v119, v243
	v_mul_f32_e32 v116, 0xbfb8aa3b, v116
	v_mul_f32_e32 v117, 0xbfb8aa3b, v117
	v_mul_f32_e32 v118, 0xbfb8aa3b, v118
	v_mul_f32_e32 v119, 0xbfb8aa3b, v119
	v_exp_f32_e32 v116, v116
	v_exp_f32_e32 v117, v117
	v_exp_f32_e32 v118, v118
	v_exp_f32_e32 v119, v119
	v_add_f32_e32 v116, 1.0, v116
	v_add_f32_e32 v117, 1.0, v117
	v_add_f32_e32 v118, 1.0, v118
	v_add_f32_e32 v119, 1.0, v119
	v_rcp_f32_e32 v116, v116
	v_rcp_f32_e32 v117, v117
	v_rcp_f32_e32 v118, v118
	v_rcp_f32_e32 v119, v119
	v_mul_f32_e32 v116, v116, v126
	v_mul_f32_e32 v117, v117, v127
	v_mul_f32_e32 v118, v118, v145
	v_mul_f32_e32 v119, v119, v148
	v_cvt_pk_bf16_f32 v116, v116, v117
	v_cvt_pk_bf16_f32 v117, v118, v119
	global_store_dwordx2 v[146:147], v[116:117], off offset:256
	s_waitcnt vmcnt(1)
	v_lshlrev_b32_e32 v118, 16, v120
	v_and_b32_e32 v119, 0xffff0000, v120
	v_lshlrev_b32_e32 v120, 16, v121
	v_and_b32_e32 v121, 0xffff0000, v121
	v_or_b32_e32 v126, 16, v144
	v_ashrrev_i32_e32 v127, 31, v126
	v_lshlrev_b64 v[116:117], 10, v[126:127]
	v_lshl_add_u64 v[116:117], s[82:83], 0, v[116:117]
	v_lshl_add_u64 v[116:117], v[116:117], 0, v[142:143]
	global_load_dwordx2 v[148:149], v[116:117], off
	v_add_f32_e32 v112, v112, v244
	v_add_f32_e32 v113, v113, v245
	v_add_f32_e32 v114, v114, v246
	v_add_f32_e32 v115, v115, v247
	v_mul_f32_e32 v112, 0xbfb8aa3b, v112
	v_mul_f32_e32 v113, 0xbfb8aa3b, v113
	v_mul_f32_e32 v114, 0xbfb8aa3b, v114
	v_mul_f32_e32 v115, 0xbfb8aa3b, v115
	v_exp_f32_e32 v112, v112
	v_exp_f32_e32 v113, v113
	v_exp_f32_e32 v114, v114
	v_exp_f32_e32 v115, v115
	v_add_f32_e32 v112, 1.0, v112
	v_add_f32_e32 v113, 1.0, v113
	v_add_f32_e32 v114, 1.0, v114
	v_add_f32_e32 v115, 1.0, v115
	v_rcp_f32_e32 v112, v112
	v_rcp_f32_e32 v113, v113
	v_rcp_f32_e32 v114, v114
	v_rcp_f32_e32 v115, v115
	v_mul_f32_e32 v112, v112, v118
	v_mul_f32_e32 v113, v113, v119
	v_mul_f32_e32 v114, v114, v120
	v_mul_f32_e32 v115, v115, v121
	v_cvt_pk_bf16_f32 v112, v112, v113
	v_cvt_pk_bf16_f32 v113, v114, v115
	global_store_dwordx2 v[146:147], v[112:113], off offset:288
	v_lshlrev_b64 v[112:113], 12, v[126:127]
	v_lshl_add_u64 v[112:113], s[18:19], 0, v[112:113]
	global_load_dwordx2 v[114:115], v[116:117], off offset:32
	s_waitcnt vmcnt(2)
	v_lshlrev_b32_e32 v122, 16, v148
	v_and_b32_e32 v123, 0xffff0000, v148
	v_lshl_add_u64 v[112:113], v[112:113], 0, v[142:143]
	v_lshlrev_b32_e32 v124, 16, v149
	v_and_b32_e32 v125, 0xffff0000, v149
	v_add_f32_e32 v108, v108, v232
	v_add_f32_e32 v109, v109, v233
	v_add_f32_e32 v110, v110, v234
	v_add_f32_e32 v111, v111, v235
	v_mul_f32_e32 v108, 0xbfb8aa3b, v108
	v_mul_f32_e32 v109, 0xbfb8aa3b, v109
	v_mul_f32_e32 v110, 0xbfb8aa3b, v110
	v_mul_f32_e32 v111, 0xbfb8aa3b, v111
	v_exp_f32_e32 v108, v108
	v_exp_f32_e32 v109, v109
	v_exp_f32_e32 v110, v110
	v_exp_f32_e32 v111, v111
	v_add_f32_e32 v108, 1.0, v108
	v_add_f32_e32 v109, 1.0, v109
	v_add_f32_e32 v110, 1.0, v110
	v_add_f32_e32 v111, 1.0, v111
	v_rcp_f32_e32 v108, v108
	v_rcp_f32_e32 v109, v109
	v_rcp_f32_e32 v110, v110
	v_rcp_f32_e32 v111, v111
	v_mul_f32_e32 v108, v108, v122
	v_mul_f32_e32 v109, v109, v123
	v_mul_f32_e32 v110, v110, v124
	v_mul_f32_e32 v111, v111, v125
	v_cvt_pk_bf16_f32 v108, v108, v109
	v_cvt_pk_bf16_f32 v109, v110, v111
	global_store_dwordx2 v[112:113], v[108:109], off
	s_waitcnt vmcnt(1)
	v_lshlrev_b32_e32 v118, 16, v114
	v_and_b32_e32 v119, 0xffff0000, v114
	v_lshlrev_b32_e32 v120, 16, v115
	v_and_b32_e32 v121, 0xffff0000, v115
	global_load_dwordx2 v[114:115], v[116:117], off offset:256
	v_add_f32_e32 v104, v104, v236
	v_add_f32_e32 v105, v105, v237
	v_add_f32_e32 v106, v106, v238
	v_add_f32_e32 v107, v107, v239
	v_mul_f32_e32 v104, 0xbfb8aa3b, v104
	v_mul_f32_e32 v105, 0xbfb8aa3b, v105
	v_mul_f32_e32 v106, 0xbfb8aa3b, v106
	v_mul_f32_e32 v107, 0xbfb8aa3b, v107
	v_exp_f32_e32 v104, v104
	v_exp_f32_e32 v105, v105
	v_exp_f32_e32 v106, v106
	v_exp_f32_e32 v107, v107
	v_add_f32_e32 v104, 1.0, v104
	v_add_f32_e32 v105, 1.0, v105
	v_add_f32_e32 v106, 1.0, v106
	v_add_f32_e32 v107, 1.0, v107
	v_rcp_f32_e32 v104, v104
	v_rcp_f32_e32 v105, v105
	v_rcp_f32_e32 v106, v106
	v_rcp_f32_e32 v107, v107
	v_mul_f32_e32 v104, v104, v118
	v_mul_f32_e32 v105, v105, v119
	v_mul_f32_e32 v106, v106, v120
	v_mul_f32_e32 v107, v107, v121
	v_cvt_pk_bf16_f32 v104, v104, v105
	v_cvt_pk_bf16_f32 v105, v106, v107
	global_store_dwordx2 v[112:113], v[104:105], off offset:32
	s_waitcnt vmcnt(1)
	v_add_f32_e32 v100, v100, v240
	v_add_f32_e32 v101, v101, v241
	v_add_f32_e32 v102, v102, v242
	v_add_f32_e32 v103, v103, v243
	v_mul_f32_e32 v100, 0xbfb8aa3b, v100
	v_mul_f32_e32 v101, 0xbfb8aa3b, v101
	v_mul_f32_e32 v102, 0xbfb8aa3b, v102
	v_mul_f32_e32 v103, 0xbfb8aa3b, v103
	v_exp_f32_e32 v100, v100
	v_exp_f32_e32 v101, v101
	v_exp_f32_e32 v102, v102
	v_exp_f32_e32 v103, v103
	v_add_f32_e32 v100, 1.0, v100
	v_add_f32_e32 v101, 1.0, v101
	v_add_f32_e32 v102, 1.0, v102
	v_add_f32_e32 v103, 1.0, v103
	v_rcp_f32_e32 v100, v100
	v_rcp_f32_e32 v101, v101
	v_rcp_f32_e32 v102, v102
	v_rcp_f32_e32 v103, v103
	global_load_dwordx2 v[104:105], v[116:117], off offset:288
	v_lshlrev_b32_e32 v110, 16, v114
	v_and_b32_e32 v111, 0xffff0000, v114
	v_lshlrev_b32_e32 v114, 16, v115
	v_and_b32_e32 v115, 0xffff0000, v115
	v_mul_f32_e32 v100, v100, v110
	v_mul_f32_e32 v101, v101, v111
	v_mul_f32_e32 v102, v102, v114
	v_mul_f32_e32 v103, v103, v115
	v_cvt_pk_bf16_f32 v100, v100, v101
	v_cvt_pk_bf16_f32 v101, v102, v103
	global_store_dwordx2 v[112:113], v[100:101], off offset:256
	v_or_b32_e32 v110, 32, v144
	v_ashrrev_i32_e32 v111, 31, v110
	v_lshlrev_b64 v[100:101], 10, v[110:111]
	v_lshl_add_u64 v[100:101], s[82:83], 0, v[100:101]
	v_lshl_add_u64 v[100:101], v[100:101], 0, v[142:143]
	global_load_dwordx2 v[114:115], v[100:101], off
	s_waitcnt vmcnt(2)
	v_lshlrev_b32_e32 v102, 16, v104
	v_and_b32_e32 v103, 0xffff0000, v104
	v_lshlrev_b32_e32 v104, 16, v105
	v_and_b32_e32 v105, 0xffff0000, v105
	v_add_f32_e32 v96, v96, v244
	v_add_f32_e32 v97, v97, v245
	v_add_f32_e32 v98, v98, v246
	v_add_f32_e32 v99, v99, v247
	v_mul_f32_e32 v96, 0xbfb8aa3b, v96
	v_mul_f32_e32 v97, 0xbfb8aa3b, v97
	v_mul_f32_e32 v98, 0xbfb8aa3b, v98
	v_mul_f32_e32 v99, 0xbfb8aa3b, v99
	v_exp_f32_e32 v96, v96
	v_exp_f32_e32 v97, v97
	v_exp_f32_e32 v98, v98
	v_exp_f32_e32 v99, v99
	v_add_f32_e32 v96, 1.0, v96
	v_add_f32_e32 v97, 1.0, v97
	v_add_f32_e32 v98, 1.0, v98
	v_add_f32_e32 v99, 1.0, v99
	v_rcp_f32_e32 v96, v96
	v_rcp_f32_e32 v97, v97
	v_rcp_f32_e32 v98, v98
	v_rcp_f32_e32 v99, v99
	v_mul_f32_e32 v96, v96, v102
	v_mul_f32_e32 v97, v97, v103
	v_mul_f32_e32 v98, v98, v104
	v_mul_f32_e32 v99, v99, v105
	v_cvt_pk_bf16_f32 v96, v96, v97
	v_cvt_pk_bf16_f32 v97, v98, v99
	global_store_dwordx2 v[112:113], v[96:97], off offset:288
	v_lshlrev_b64 v[96:97], 12, v[110:111]
	v_lshl_add_u64 v[96:97], s[18:19], 0, v[96:97]
	global_load_dwordx2 v[98:99], v[100:101], off offset:32
	s_waitcnt vmcnt(2)
	v_lshlrev_b32_e32 v106, 16, v114
	v_and_b32_e32 v107, 0xffff0000, v114
	v_lshl_add_u64 v[96:97], v[96:97], 0, v[142:143]
	v_lshlrev_b32_e32 v108, 16, v115
	v_and_b32_e32 v109, 0xffff0000, v115
	v_add_f32_e32 v92, v92, v232
	v_add_f32_e32 v93, v93, v233
	v_add_f32_e32 v94, v94, v234
	v_add_f32_e32 v95, v95, v235
	v_mul_f32_e32 v92, 0xbfb8aa3b, v92
	v_mul_f32_e32 v93, 0xbfb8aa3b, v93
	v_mul_f32_e32 v94, 0xbfb8aa3b, v94
	v_mul_f32_e32 v95, 0xbfb8aa3b, v95
	v_exp_f32_e32 v92, v92
	v_exp_f32_e32 v93, v93
	v_exp_f32_e32 v94, v94
	v_exp_f32_e32 v95, v95
	v_add_f32_e32 v92, 1.0, v92
	v_add_f32_e32 v93, 1.0, v93
	v_add_f32_e32 v94, 1.0, v94
	v_add_f32_e32 v95, 1.0, v95
	v_rcp_f32_e32 v92, v92
	v_rcp_f32_e32 v93, v93
	v_rcp_f32_e32 v94, v94
	v_rcp_f32_e32 v95, v95
	v_mul_f32_e32 v92, v92, v106
	v_mul_f32_e32 v93, v93, v107
	v_mul_f32_e32 v94, v94, v108
	v_mul_f32_e32 v95, v95, v109
	v_cvt_pk_bf16_f32 v92, v92, v93
	v_cvt_pk_bf16_f32 v93, v94, v95
	global_store_dwordx2 v[96:97], v[92:93], off
	s_waitcnt vmcnt(1)
	v_lshlrev_b32_e32 v102, 16, v98
	v_and_b32_e32 v103, 0xffff0000, v98
	v_lshlrev_b32_e32 v104, 16, v99
	v_and_b32_e32 v105, 0xffff0000, v99
	global_load_dwordx2 v[98:99], v[100:101], off offset:256
	v_add_f32_e32 v88, v88, v236
	v_add_f32_e32 v89, v89, v237
	v_add_f32_e32 v90, v90, v238
	v_add_f32_e32 v91, v91, v239
	v_mul_f32_e32 v88, 0xbfb8aa3b, v88
	v_mul_f32_e32 v89, 0xbfb8aa3b, v89
	v_mul_f32_e32 v90, 0xbfb8aa3b, v90
	v_mul_f32_e32 v91, 0xbfb8aa3b, v91
	v_exp_f32_e32 v88, v88
	v_exp_f32_e32 v89, v89
	v_exp_f32_e32 v90, v90
	v_exp_f32_e32 v91, v91
	v_add_f32_e32 v88, 1.0, v88
	v_add_f32_e32 v89, 1.0, v89
	v_add_f32_e32 v90, 1.0, v90
	v_add_f32_e32 v91, 1.0, v91
	v_rcp_f32_e32 v88, v88
	v_rcp_f32_e32 v89, v89
	v_rcp_f32_e32 v90, v90
	v_rcp_f32_e32 v91, v91
	v_mul_f32_e32 v88, v88, v102
	v_mul_f32_e32 v89, v89, v103
	v_mul_f32_e32 v90, v90, v104
	v_mul_f32_e32 v91, v91, v105
	v_cvt_pk_bf16_f32 v88, v88, v89
	v_cvt_pk_bf16_f32 v89, v90, v91
	global_store_dwordx2 v[96:97], v[88:89], off offset:32
	s_waitcnt vmcnt(1)
	v_add_f32_e32 v84, v84, v240
	v_add_f32_e32 v85, v85, v241
	v_add_f32_e32 v86, v86, v242
	v_add_f32_e32 v87, v87, v243
	v_mul_f32_e32 v84, 0xbfb8aa3b, v84
	v_mul_f32_e32 v85, 0xbfb8aa3b, v85
	v_mul_f32_e32 v86, 0xbfb8aa3b, v86
	v_mul_f32_e32 v87, 0xbfb8aa3b, v87
	v_exp_f32_e32 v84, v84
	v_exp_f32_e32 v85, v85
	v_exp_f32_e32 v86, v86
	v_exp_f32_e32 v87, v87
	v_add_f32_e32 v84, 1.0, v84
	v_add_f32_e32 v85, 1.0, v85
	v_add_f32_e32 v86, 1.0, v86
	v_add_f32_e32 v87, 1.0, v87
	v_rcp_f32_e32 v84, v84
	v_rcp_f32_e32 v85, v85
	v_rcp_f32_e32 v86, v86
	v_rcp_f32_e32 v87, v87
	global_load_dwordx2 v[88:89], v[100:101], off offset:288
	v_lshlrev_b32_e32 v94, 16, v98
	v_and_b32_e32 v95, 0xffff0000, v98
	v_lshlrev_b32_e32 v98, 16, v99
	v_and_b32_e32 v99, 0xffff0000, v99
	v_mul_f32_e32 v84, v84, v94
	v_mul_f32_e32 v85, v85, v95
	v_mul_f32_e32 v86, v86, v98
	v_mul_f32_e32 v87, v87, v99
	v_cvt_pk_bf16_f32 v84, v84, v85
	v_cvt_pk_bf16_f32 v85, v86, v87
	global_store_dwordx2 v[96:97], v[84:85], off offset:256
	v_or_b32_e32 v94, 48, v144
	v_ashrrev_i32_e32 v95, 31, v94
	v_lshlrev_b64 v[84:85], 10, v[94:95]
	v_lshl_add_u64 v[84:85], s[82:83], 0, v[84:85]
	v_lshl_add_u64 v[84:85], v[84:85], 0, v[142:143]
	global_load_dwordx2 v[98:99], v[84:85], off
	s_waitcnt vmcnt(2)
	v_lshlrev_b32_e32 v86, 16, v88
	v_and_b32_e32 v87, 0xffff0000, v88
	v_lshlrev_b32_e32 v88, 16, v89
	v_and_b32_e32 v89, 0xffff0000, v89
	v_add_f32_e32 v80, v80, v244
	v_add_f32_e32 v81, v81, v245
	v_add_f32_e32 v82, v82, v246
	v_add_f32_e32 v83, v83, v247
	v_mul_f32_e32 v80, 0xbfb8aa3b, v80
	v_mul_f32_e32 v81, 0xbfb8aa3b, v81
	v_mul_f32_e32 v82, 0xbfb8aa3b, v82
	v_mul_f32_e32 v83, 0xbfb8aa3b, v83
	v_exp_f32_e32 v80, v80
	v_exp_f32_e32 v81, v81
	v_exp_f32_e32 v82, v82
	v_exp_f32_e32 v83, v83
	v_add_f32_e32 v80, 1.0, v80
	v_add_f32_e32 v81, 1.0, v81
	v_add_f32_e32 v82, 1.0, v82
	v_add_f32_e32 v83, 1.0, v83
	v_rcp_f32_e32 v80, v80
	v_rcp_f32_e32 v81, v81
	v_rcp_f32_e32 v82, v82
	v_rcp_f32_e32 v83, v83
	v_mul_f32_e32 v80, v80, v86
	v_mul_f32_e32 v81, v81, v87
	v_mul_f32_e32 v82, v82, v88
	v_mul_f32_e32 v83, v83, v89
	v_cvt_pk_bf16_f32 v80, v80, v81
	v_cvt_pk_bf16_f32 v81, v82, v83
	global_store_dwordx2 v[96:97], v[80:81], off offset:288
	v_lshlrev_b64 v[80:81], 12, v[94:95]
	v_lshl_add_u64 v[80:81], s[18:19], 0, v[80:81]
	global_load_dwordx2 v[82:83], v[84:85], off offset:32
	s_waitcnt vmcnt(2)
	v_lshlrev_b32_e32 v90, 16, v98
	v_and_b32_e32 v91, 0xffff0000, v98
	v_lshl_add_u64 v[80:81], v[80:81], 0, v[142:143]
	v_lshlrev_b32_e32 v92, 16, v99
	v_and_b32_e32 v93, 0xffff0000, v99
	v_add_f32_e32 v76, v76, v232
	v_add_f32_e32 v77, v77, v233
	v_add_f32_e32 v78, v78, v234
	v_add_f32_e32 v79, v79, v235
	v_mul_f32_e32 v76, 0xbfb8aa3b, v76
	v_mul_f32_e32 v77, 0xbfb8aa3b, v77
	v_mul_f32_e32 v78, 0xbfb8aa3b, v78
	v_mul_f32_e32 v79, 0xbfb8aa3b, v79
	v_exp_f32_e32 v76, v76
	v_exp_f32_e32 v77, v77
	v_exp_f32_e32 v78, v78
	v_exp_f32_e32 v79, v79
	v_add_f32_e32 v76, 1.0, v76
	v_add_f32_e32 v77, 1.0, v77
	v_add_f32_e32 v78, 1.0, v78
	v_add_f32_e32 v79, 1.0, v79
	v_rcp_f32_e32 v76, v76
	v_rcp_f32_e32 v77, v77
	v_rcp_f32_e32 v78, v78
	v_rcp_f32_e32 v79, v79
	v_mul_f32_e32 v76, v76, v90
	v_mul_f32_e32 v77, v77, v91
	v_mul_f32_e32 v78, v78, v92
	v_mul_f32_e32 v79, v79, v93
	v_cvt_pk_bf16_f32 v76, v76, v77
	v_cvt_pk_bf16_f32 v77, v78, v79
	global_store_dwordx2 v[80:81], v[76:77], off
	s_waitcnt vmcnt(1)
	v_lshlrev_b32_e32 v86, 16, v82
	v_and_b32_e32 v87, 0xffff0000, v82
	v_lshlrev_b32_e32 v88, 16, v83
	v_and_b32_e32 v89, 0xffff0000, v83
	global_load_dwordx2 v[82:83], v[84:85], off offset:256
	v_add_f32_e32 v72, v72, v236
	v_add_f32_e32 v73, v73, v237
	v_add_f32_e32 v74, v74, v238
	v_add_f32_e32 v75, v75, v239
	v_mul_f32_e32 v72, 0xbfb8aa3b, v72
	v_mul_f32_e32 v73, 0xbfb8aa3b, v73
	v_mul_f32_e32 v74, 0xbfb8aa3b, v74
	v_mul_f32_e32 v75, 0xbfb8aa3b, v75
	v_exp_f32_e32 v72, v72
	v_exp_f32_e32 v73, v73
	v_exp_f32_e32 v74, v74
	v_exp_f32_e32 v75, v75
	v_add_f32_e32 v72, 1.0, v72
	v_add_f32_e32 v73, 1.0, v73
	v_add_f32_e32 v74, 1.0, v74
	v_add_f32_e32 v75, 1.0, v75
	v_rcp_f32_e32 v72, v72
	v_rcp_f32_e32 v73, v73
	v_rcp_f32_e32 v74, v74
	v_rcp_f32_e32 v75, v75
	v_mul_f32_e32 v72, v72, v86
	v_mul_f32_e32 v73, v73, v87
	v_mul_f32_e32 v74, v74, v88
	v_mul_f32_e32 v75, v75, v89
	v_cvt_pk_bf16_f32 v72, v72, v73
	v_cvt_pk_bf16_f32 v73, v74, v75
	global_store_dwordx2 v[80:81], v[72:73], off offset:32
	s_waitcnt vmcnt(1)
	v_add_f32_e32 v68, v68, v240
	v_add_f32_e32 v69, v69, v241
	v_add_f32_e32 v70, v70, v242
	v_add_f32_e32 v71, v71, v243
	v_mul_f32_e32 v68, 0xbfb8aa3b, v68
	v_mul_f32_e32 v69, 0xbfb8aa3b, v69
	v_mul_f32_e32 v70, 0xbfb8aa3b, v70
	v_mul_f32_e32 v71, 0xbfb8aa3b, v71
	v_exp_f32_e32 v68, v68
	v_exp_f32_e32 v69, v69
	v_exp_f32_e32 v70, v70
	v_exp_f32_e32 v71, v71
	v_add_f32_e32 v68, 1.0, v68
	v_add_f32_e32 v69, 1.0, v69
	v_add_f32_e32 v70, 1.0, v70
	v_add_f32_e32 v71, 1.0, v71
	v_rcp_f32_e32 v68, v68
	v_rcp_f32_e32 v69, v69
	v_rcp_f32_e32 v70, v70
	v_rcp_f32_e32 v71, v71
	global_load_dwordx2 v[72:73], v[84:85], off offset:288
	v_lshlrev_b32_e32 v78, 16, v82
	v_and_b32_e32 v79, 0xffff0000, v82
	v_lshlrev_b32_e32 v82, 16, v83
	v_and_b32_e32 v83, 0xffff0000, v83
	v_mul_f32_e32 v68, v68, v78
	v_mul_f32_e32 v69, v69, v79
	v_mul_f32_e32 v70, v70, v82
	v_mul_f32_e32 v71, v71, v83
	v_cvt_pk_bf16_f32 v68, v68, v69
	v_cvt_pk_bf16_f32 v69, v70, v71
	global_store_dwordx2 v[80:81], v[68:69], off offset:256
	v_add_u32_e32 v78, 0x80, v144
	v_ashrrev_i32_e32 v79, 31, v78
	v_lshlrev_b64 v[68:69], 10, v[78:79]
	v_lshl_add_u64 v[68:69], s[82:83], 0, v[68:69]
	v_lshl_add_u64 v[68:69], v[68:69], 0, v[142:143]
	global_load_dwordx2 v[82:83], v[68:69], off
	s_waitcnt vmcnt(2)
	v_lshlrev_b32_e32 v70, 16, v72
	v_and_b32_e32 v71, 0xffff0000, v72
	v_lshlrev_b32_e32 v72, 16, v73
	v_and_b32_e32 v73, 0xffff0000, v73
	v_add_f32_e32 v64, v64, v244
	v_add_f32_e32 v65, v65, v245
	v_add_f32_e32 v66, v66, v246
	v_add_f32_e32 v67, v67, v247
	v_mul_f32_e32 v64, 0xbfb8aa3b, v64
	v_mul_f32_e32 v65, 0xbfb8aa3b, v65
	v_mul_f32_e32 v66, 0xbfb8aa3b, v66
	v_mul_f32_e32 v67, 0xbfb8aa3b, v67
	v_exp_f32_e32 v64, v64
	v_exp_f32_e32 v65, v65
	v_exp_f32_e32 v66, v66
	v_exp_f32_e32 v67, v67
	v_add_f32_e32 v64, 1.0, v64
	v_add_f32_e32 v65, 1.0, v65
	v_add_f32_e32 v66, 1.0, v66
	v_add_f32_e32 v67, 1.0, v67
	v_rcp_f32_e32 v64, v64
	v_rcp_f32_e32 v65, v65
	v_rcp_f32_e32 v66, v66
	v_rcp_f32_e32 v67, v67
	v_mul_f32_e32 v64, v64, v70
	v_mul_f32_e32 v65, v65, v71
	v_mul_f32_e32 v66, v66, v72
	v_mul_f32_e32 v67, v67, v73
	v_cvt_pk_bf16_f32 v64, v64, v65
	v_cvt_pk_bf16_f32 v65, v66, v67
	global_store_dwordx2 v[80:81], v[64:65], off offset:288
	v_lshlrev_b64 v[64:65], 12, v[78:79]
	v_lshl_add_u64 v[64:65], s[18:19], 0, v[64:65]
	global_load_dwordx2 v[66:67], v[68:69], off offset:32
	s_waitcnt vmcnt(2)
	v_lshlrev_b32_e32 v74, 16, v82
	v_and_b32_e32 v75, 0xffff0000, v82
	v_lshl_add_u64 v[64:65], v[64:65], 0, v[142:143]
	v_lshlrev_b32_e32 v76, 16, v83
	v_and_b32_e32 v77, 0xffff0000, v83
	v_add_f32_e32 v60, v60, v232
	v_add_f32_e32 v61, v61, v233
	v_add_f32_e32 v62, v62, v234
	v_add_f32_e32 v63, v63, v235
	v_mul_f32_e32 v60, 0xbfb8aa3b, v60
	v_mul_f32_e32 v61, 0xbfb8aa3b, v61
	v_mul_f32_e32 v62, 0xbfb8aa3b, v62
	v_mul_f32_e32 v63, 0xbfb8aa3b, v63
	v_exp_f32_e32 v60, v60
	v_exp_f32_e32 v61, v61
	v_exp_f32_e32 v62, v62
	v_exp_f32_e32 v63, v63
	v_add_f32_e32 v60, 1.0, v60
	v_add_f32_e32 v61, 1.0, v61
	v_add_f32_e32 v62, 1.0, v62
	v_add_f32_e32 v63, 1.0, v63
	v_rcp_f32_e32 v60, v60
	v_rcp_f32_e32 v61, v61
	v_rcp_f32_e32 v62, v62
	v_rcp_f32_e32 v63, v63
	v_mul_f32_e32 v60, v60, v74
	v_mul_f32_e32 v61, v61, v75
	v_mul_f32_e32 v62, v62, v76
	v_mul_f32_e32 v63, v63, v77
	v_cvt_pk_bf16_f32 v60, v60, v61
	v_cvt_pk_bf16_f32 v61, v62, v63
	global_store_dwordx2 v[64:65], v[60:61], off
	s_waitcnt vmcnt(1)
	v_lshlrev_b32_e32 v70, 16, v66
	v_and_b32_e32 v71, 0xffff0000, v66
	v_lshlrev_b32_e32 v72, 16, v67
	v_and_b32_e32 v73, 0xffff0000, v67
	global_load_dwordx2 v[66:67], v[68:69], off offset:256
	v_add_f32_e32 v56, v56, v236
	v_add_f32_e32 v57, v57, v237
	v_add_f32_e32 v58, v58, v238
	v_add_f32_e32 v59, v59, v239
	v_mul_f32_e32 v56, 0xbfb8aa3b, v56
	v_mul_f32_e32 v57, 0xbfb8aa3b, v57
	v_mul_f32_e32 v58, 0xbfb8aa3b, v58
	v_mul_f32_e32 v59, 0xbfb8aa3b, v59
	v_exp_f32_e32 v56, v56
	v_exp_f32_e32 v57, v57
	v_exp_f32_e32 v58, v58
	v_exp_f32_e32 v59, v59
	v_add_f32_e32 v56, 1.0, v56
	v_add_f32_e32 v57, 1.0, v57
	v_add_f32_e32 v58, 1.0, v58
	v_add_f32_e32 v59, 1.0, v59
	v_rcp_f32_e32 v56, v56
	v_rcp_f32_e32 v57, v57
	v_rcp_f32_e32 v58, v58
	v_rcp_f32_e32 v59, v59
	v_mul_f32_e32 v56, v56, v70
	v_mul_f32_e32 v57, v57, v71
	v_mul_f32_e32 v58, v58, v72
	v_mul_f32_e32 v59, v59, v73
	v_cvt_pk_bf16_f32 v56, v56, v57
	v_cvt_pk_bf16_f32 v57, v58, v59
	global_store_dwordx2 v[64:65], v[56:57], off offset:32
	s_waitcnt vmcnt(1)
	v_add_f32_e32 v52, v52, v240
	v_add_f32_e32 v53, v53, v241
	v_add_f32_e32 v54, v54, v242
	v_add_f32_e32 v55, v55, v243
	v_mul_f32_e32 v52, 0xbfb8aa3b, v52
	v_mul_f32_e32 v53, 0xbfb8aa3b, v53
	v_mul_f32_e32 v54, 0xbfb8aa3b, v54
	v_mul_f32_e32 v55, 0xbfb8aa3b, v55
	v_exp_f32_e32 v52, v52
	v_exp_f32_e32 v53, v53
	v_exp_f32_e32 v54, v54
	v_exp_f32_e32 v55, v55
	v_add_f32_e32 v52, 1.0, v52
	v_add_f32_e32 v53, 1.0, v53
	v_add_f32_e32 v54, 1.0, v54
	v_add_f32_e32 v55, 1.0, v55
	v_rcp_f32_e32 v52, v52
	v_rcp_f32_e32 v53, v53
	v_rcp_f32_e32 v54, v54
	v_rcp_f32_e32 v55, v55
	global_load_dwordx2 v[56:57], v[68:69], off offset:288
	v_lshlrev_b32_e32 v62, 16, v66
	v_and_b32_e32 v63, 0xffff0000, v66
	v_lshlrev_b32_e32 v66, 16, v67
	v_and_b32_e32 v67, 0xffff0000, v67
	v_mul_f32_e32 v52, v52, v62
	v_mul_f32_e32 v53, v53, v63
	v_mul_f32_e32 v54, v54, v66
	v_mul_f32_e32 v55, v55, v67
	v_cvt_pk_bf16_f32 v52, v52, v53
	v_cvt_pk_bf16_f32 v53, v54, v55
	global_store_dwordx2 v[64:65], v[52:53], off offset:256
	v_add_u32_e32 v62, 0x90, v144
	v_ashrrev_i32_e32 v63, 31, v62
	v_lshlrev_b64 v[52:53], 10, v[62:63]
	v_lshl_add_u64 v[52:53], s[82:83], 0, v[52:53]
	v_lshl_add_u64 v[52:53], v[52:53], 0, v[142:143]
	global_load_dwordx2 v[66:67], v[52:53], off
	s_waitcnt vmcnt(2)
	v_lshlrev_b32_e32 v54, 16, v56
	v_and_b32_e32 v55, 0xffff0000, v56
	v_lshlrev_b32_e32 v56, 16, v57
	v_and_b32_e32 v57, 0xffff0000, v57
	v_add_f32_e32 v48, v48, v244
	v_add_f32_e32 v49, v49, v245
	v_add_f32_e32 v50, v50, v246
	v_add_f32_e32 v51, v51, v247
	v_mul_f32_e32 v48, 0xbfb8aa3b, v48
	v_mul_f32_e32 v49, 0xbfb8aa3b, v49
	v_mul_f32_e32 v50, 0xbfb8aa3b, v50
	v_mul_f32_e32 v51, 0xbfb8aa3b, v51
	v_exp_f32_e32 v48, v48
	v_exp_f32_e32 v49, v49
	v_exp_f32_e32 v50, v50
	v_exp_f32_e32 v51, v51
	v_add_f32_e32 v48, 1.0, v48
	v_add_f32_e32 v49, 1.0, v49
	v_add_f32_e32 v50, 1.0, v50
	v_add_f32_e32 v51, 1.0, v51
	v_rcp_f32_e32 v48, v48
	v_rcp_f32_e32 v49, v49
	v_rcp_f32_e32 v50, v50
	v_rcp_f32_e32 v51, v51
	v_mul_f32_e32 v48, v48, v54
	v_mul_f32_e32 v49, v49, v55
	v_mul_f32_e32 v50, v50, v56
	v_mul_f32_e32 v51, v51, v57
	v_cvt_pk_bf16_f32 v48, v48, v49
	v_cvt_pk_bf16_f32 v49, v50, v51
	global_store_dwordx2 v[64:65], v[48:49], off offset:288
	v_lshlrev_b64 v[48:49], 12, v[62:63]
	v_lshl_add_u64 v[48:49], s[18:19], 0, v[48:49]
	global_load_dwordx2 v[50:51], v[52:53], off offset:32
	s_waitcnt vmcnt(2)
	v_lshlrev_b32_e32 v58, 16, v66
	v_and_b32_e32 v59, 0xffff0000, v66
	v_lshl_add_u64 v[48:49], v[48:49], 0, v[142:143]
	v_lshlrev_b32_e32 v60, 16, v67
	v_and_b32_e32 v61, 0xffff0000, v67
	v_add_f32_e32 v44, v44, v232
	v_add_f32_e32 v45, v45, v233
	v_add_f32_e32 v46, v46, v234
	v_add_f32_e32 v47, v47, v235
	v_mul_f32_e32 v44, 0xbfb8aa3b, v44
	v_mul_f32_e32 v45, 0xbfb8aa3b, v45
	v_mul_f32_e32 v46, 0xbfb8aa3b, v46
	v_mul_f32_e32 v47, 0xbfb8aa3b, v47
	v_exp_f32_e32 v44, v44
	v_exp_f32_e32 v45, v45
	v_exp_f32_e32 v46, v46
	v_exp_f32_e32 v47, v47
	v_add_f32_e32 v44, 1.0, v44
	v_add_f32_e32 v45, 1.0, v45
	v_add_f32_e32 v46, 1.0, v46
	v_add_f32_e32 v47, 1.0, v47
	v_rcp_f32_e32 v44, v44
	v_rcp_f32_e32 v45, v45
	v_rcp_f32_e32 v46, v46
	v_rcp_f32_e32 v47, v47
	v_mul_f32_e32 v44, v44, v58
	v_mul_f32_e32 v45, v45, v59
	v_mul_f32_e32 v46, v46, v60
	v_mul_f32_e32 v47, v47, v61
	v_cvt_pk_bf16_f32 v44, v44, v45
	v_cvt_pk_bf16_f32 v45, v46, v47
	global_store_dwordx2 v[48:49], v[44:45], off
	s_waitcnt vmcnt(1)
	v_lshlrev_b32_e32 v54, 16, v50
	v_and_b32_e32 v55, 0xffff0000, v50
	v_lshlrev_b32_e32 v56, 16, v51
	v_and_b32_e32 v57, 0xffff0000, v51
	global_load_dwordx2 v[50:51], v[52:53], off offset:256
	v_add_f32_e32 v40, v40, v236
	v_add_f32_e32 v41, v41, v237
	v_add_f32_e32 v42, v42, v238
	v_add_f32_e32 v43, v43, v239
	v_mul_f32_e32 v40, 0xbfb8aa3b, v40
	v_mul_f32_e32 v41, 0xbfb8aa3b, v41
	v_mul_f32_e32 v42, 0xbfb8aa3b, v42
	v_mul_f32_e32 v43, 0xbfb8aa3b, v43
	v_exp_f32_e32 v40, v40
	v_exp_f32_e32 v41, v41
	v_exp_f32_e32 v42, v42
	v_exp_f32_e32 v43, v43
	v_add_f32_e32 v40, 1.0, v40
	v_add_f32_e32 v41, 1.0, v41
	v_add_f32_e32 v42, 1.0, v42
	v_add_f32_e32 v43, 1.0, v43
	v_rcp_f32_e32 v40, v40
	v_rcp_f32_e32 v41, v41
	v_rcp_f32_e32 v42, v42
	v_rcp_f32_e32 v43, v43
	v_mul_f32_e32 v40, v40, v54
	v_mul_f32_e32 v41, v41, v55
	v_mul_f32_e32 v42, v42, v56
	v_mul_f32_e32 v43, v43, v57
	v_cvt_pk_bf16_f32 v40, v40, v41
	v_cvt_pk_bf16_f32 v41, v42, v43
	global_store_dwordx2 v[48:49], v[40:41], off offset:32
	s_waitcnt vmcnt(1)
	v_add_f32_e32 v36, v36, v240
	v_add_f32_e32 v37, v37, v241
	v_add_f32_e32 v38, v38, v242
	v_add_f32_e32 v39, v39, v243
	v_mul_f32_e32 v36, 0xbfb8aa3b, v36
	v_mul_f32_e32 v37, 0xbfb8aa3b, v37
	v_mul_f32_e32 v38, 0xbfb8aa3b, v38
	v_mul_f32_e32 v39, 0xbfb8aa3b, v39
	v_exp_f32_e32 v36, v36
	v_exp_f32_e32 v37, v37
	v_exp_f32_e32 v38, v38
	v_exp_f32_e32 v39, v39
	v_add_f32_e32 v36, 1.0, v36
	v_add_f32_e32 v37, 1.0, v37
	v_add_f32_e32 v38, 1.0, v38
	v_add_f32_e32 v39, 1.0, v39
	v_rcp_f32_e32 v36, v36
	v_rcp_f32_e32 v37, v37
	v_rcp_f32_e32 v38, v38
	v_rcp_f32_e32 v39, v39
	global_load_dwordx2 v[40:41], v[52:53], off offset:288
	v_lshlrev_b32_e32 v46, 16, v50
	v_and_b32_e32 v47, 0xffff0000, v50
	v_lshlrev_b32_e32 v50, 16, v51
	v_and_b32_e32 v51, 0xffff0000, v51
	v_mul_f32_e32 v36, v36, v46
	v_mul_f32_e32 v37, v37, v47
	v_mul_f32_e32 v38, v38, v50
	v_mul_f32_e32 v39, v39, v51
	v_cvt_pk_bf16_f32 v36, v36, v37
	v_cvt_pk_bf16_f32 v37, v38, v39
	global_store_dwordx2 v[48:49], v[36:37], off offset:256
	v_add_u32_e32 v46, 0xa0, v144
	v_ashrrev_i32_e32 v47, 31, v46
	v_lshlrev_b64 v[36:37], 10, v[46:47]
	v_lshl_add_u64 v[36:37], s[82:83], 0, v[36:37]
	v_lshl_add_u64 v[36:37], v[36:37], 0, v[142:143]
	global_load_dwordx2 v[50:51], v[36:37], off
	s_waitcnt vmcnt(2)
	v_lshlrev_b32_e32 v38, 16, v40
	v_and_b32_e32 v39, 0xffff0000, v40
	v_lshlrev_b32_e32 v40, 16, v41
	v_and_b32_e32 v41, 0xffff0000, v41
	v_add_f32_e32 v32, v32, v244
	v_add_f32_e32 v33, v33, v245
	v_add_f32_e32 v34, v34, v246
	v_add_f32_e32 v35, v35, v247
	v_mul_f32_e32 v32, 0xbfb8aa3b, v32
	v_mul_f32_e32 v33, 0xbfb8aa3b, v33
	v_mul_f32_e32 v34, 0xbfb8aa3b, v34
	v_mul_f32_e32 v35, 0xbfb8aa3b, v35
	v_exp_f32_e32 v32, v32
	v_exp_f32_e32 v33, v33
	v_exp_f32_e32 v34, v34
	v_exp_f32_e32 v35, v35
	v_add_f32_e32 v32, 1.0, v32
	v_add_f32_e32 v33, 1.0, v33
	v_add_f32_e32 v34, 1.0, v34
	v_add_f32_e32 v35, 1.0, v35
	v_rcp_f32_e32 v32, v32
	v_rcp_f32_e32 v33, v33
	v_rcp_f32_e32 v34, v34
	v_rcp_f32_e32 v35, v35
	v_mul_f32_e32 v32, v32, v38
	v_mul_f32_e32 v33, v33, v39
	v_mul_f32_e32 v34, v34, v40
	v_mul_f32_e32 v35, v35, v41
	v_cvt_pk_bf16_f32 v32, v32, v33
	v_cvt_pk_bf16_f32 v33, v34, v35
	global_store_dwordx2 v[48:49], v[32:33], off offset:288
	v_lshlrev_b64 v[32:33], 12, v[46:47]
	v_lshl_add_u64 v[32:33], s[18:19], 0, v[32:33]
	global_load_dwordx2 v[34:35], v[36:37], off offset:32
	s_waitcnt vmcnt(2)
	v_lshlrev_b32_e32 v42, 16, v50
	v_and_b32_e32 v43, 0xffff0000, v50
	v_lshl_add_u64 v[32:33], v[32:33], 0, v[142:143]
	v_lshlrev_b32_e32 v44, 16, v51
	v_and_b32_e32 v45, 0xffff0000, v51
	v_add_f32_e32 v28, v28, v232
	v_add_f32_e32 v29, v29, v233
	v_add_f32_e32 v30, v30, v234
	v_add_f32_e32 v31, v31, v235
	v_mul_f32_e32 v28, 0xbfb8aa3b, v28
	v_mul_f32_e32 v29, 0xbfb8aa3b, v29
	v_mul_f32_e32 v30, 0xbfb8aa3b, v30
	v_mul_f32_e32 v31, 0xbfb8aa3b, v31
	v_exp_f32_e32 v28, v28
	v_exp_f32_e32 v29, v29
	v_exp_f32_e32 v30, v30
	v_exp_f32_e32 v31, v31
	v_add_f32_e32 v28, 1.0, v28
	v_add_f32_e32 v29, 1.0, v29
	v_add_f32_e32 v30, 1.0, v30
	v_add_f32_e32 v31, 1.0, v31
	v_rcp_f32_e32 v28, v28
	v_rcp_f32_e32 v29, v29
	v_rcp_f32_e32 v30, v30
	v_rcp_f32_e32 v31, v31
	v_mul_f32_e32 v28, v28, v42
	v_mul_f32_e32 v29, v29, v43
	v_mul_f32_e32 v30, v30, v44
	v_mul_f32_e32 v31, v31, v45
	v_cvt_pk_bf16_f32 v28, v28, v29
	v_cvt_pk_bf16_f32 v29, v30, v31
	global_store_dwordx2 v[32:33], v[28:29], off
	s_waitcnt vmcnt(1)
	v_lshlrev_b32_e32 v38, 16, v34
	v_and_b32_e32 v39, 0xffff0000, v34
	v_lshlrev_b32_e32 v40, 16, v35
	v_and_b32_e32 v41, 0xffff0000, v35
	global_load_dwordx2 v[34:35], v[36:37], off offset:256
	v_add_f32_e32 v24, v24, v236
	v_add_f32_e32 v25, v25, v237
	v_add_f32_e32 v26, v26, v238
	v_add_f32_e32 v27, v27, v239
	v_mul_f32_e32 v24, 0xbfb8aa3b, v24
	v_mul_f32_e32 v25, 0xbfb8aa3b, v25
	v_mul_f32_e32 v26, 0xbfb8aa3b, v26
	v_mul_f32_e32 v27, 0xbfb8aa3b, v27
	v_exp_f32_e32 v24, v24
	v_exp_f32_e32 v25, v25
	v_exp_f32_e32 v26, v26
	v_exp_f32_e32 v27, v27
	v_add_f32_e32 v24, 1.0, v24
	v_add_f32_e32 v25, 1.0, v25
	v_add_f32_e32 v26, 1.0, v26
	v_add_f32_e32 v27, 1.0, v27
	v_rcp_f32_e32 v24, v24
	v_rcp_f32_e32 v25, v25
	v_rcp_f32_e32 v26, v26
	v_rcp_f32_e32 v27, v27
	v_mul_f32_e32 v24, v24, v38
	v_mul_f32_e32 v25, v25, v39
	v_mul_f32_e32 v26, v26, v40
	v_mul_f32_e32 v27, v27, v41
	v_cvt_pk_bf16_f32 v24, v24, v25
	v_cvt_pk_bf16_f32 v25, v26, v27
	global_store_dwordx2 v[32:33], v[24:25], off offset:32
	s_waitcnt vmcnt(1)
	v_add_f32_e32 v20, v20, v240
	v_add_f32_e32 v21, v21, v241
	v_add_f32_e32 v22, v22, v242
	v_add_f32_e32 v23, v23, v243
	v_mul_f32_e32 v20, 0xbfb8aa3b, v20
	v_mul_f32_e32 v21, 0xbfb8aa3b, v21
	v_mul_f32_e32 v22, 0xbfb8aa3b, v22
	v_mul_f32_e32 v23, 0xbfb8aa3b, v23
	v_exp_f32_e32 v20, v20
	v_exp_f32_e32 v21, v21
	v_exp_f32_e32 v22, v22
	v_exp_f32_e32 v23, v23
	v_add_f32_e32 v20, 1.0, v20
	v_add_f32_e32 v21, 1.0, v21
	v_add_f32_e32 v22, 1.0, v22
	v_add_f32_e32 v23, 1.0, v23
	v_rcp_f32_e32 v20, v20
	v_rcp_f32_e32 v21, v21
	v_rcp_f32_e32 v22, v22
	v_rcp_f32_e32 v23, v23
	global_load_dwordx2 v[24:25], v[36:37], off offset:288
	v_lshlrev_b32_e32 v30, 16, v34
	v_and_b32_e32 v31, 0xffff0000, v34
	v_lshlrev_b32_e32 v34, 16, v35
	v_and_b32_e32 v35, 0xffff0000, v35
	v_mul_f32_e32 v20, v20, v30
	v_mul_f32_e32 v21, v21, v31
	v_mul_f32_e32 v22, v22, v34
	v_mul_f32_e32 v23, v23, v35
	v_cvt_pk_bf16_f32 v20, v20, v21
	v_cvt_pk_bf16_f32 v21, v22, v23
	global_store_dwordx2 v[32:33], v[20:21], off offset:256
	v_add_u32_e32 v30, 0xb0, v144
	v_ashrrev_i32_e32 v31, 31, v30
	v_lshlrev_b64 v[20:21], 10, v[30:31]
	v_lshl_add_u64 v[20:21], s[82:83], 0, v[20:21]
	v_lshl_add_u64 v[20:21], v[20:21], 0, v[142:143]
	global_load_dwordx2 v[34:35], v[20:21], off
	s_waitcnt vmcnt(2)
	v_lshlrev_b32_e32 v22, 16, v24
	v_and_b32_e32 v23, 0xffff0000, v24
	v_lshlrev_b32_e32 v24, 16, v25
	v_and_b32_e32 v25, 0xffff0000, v25
	v_add_f32_e32 v16, v16, v244
	v_add_f32_e32 v17, v17, v245
	v_add_f32_e32 v18, v18, v246
	v_add_f32_e32 v19, v19, v247
	v_mul_f32_e32 v16, 0xbfb8aa3b, v16
	v_mul_f32_e32 v17, 0xbfb8aa3b, v17
	v_mul_f32_e32 v18, 0xbfb8aa3b, v18
	v_mul_f32_e32 v19, 0xbfb8aa3b, v19
	v_exp_f32_e32 v16, v16
	v_exp_f32_e32 v17, v17
	v_exp_f32_e32 v18, v18
	v_exp_f32_e32 v19, v19
	v_add_f32_e32 v16, 1.0, v16
	v_add_f32_e32 v17, 1.0, v17
	v_add_f32_e32 v18, 1.0, v18
	v_add_f32_e32 v19, 1.0, v19
	v_rcp_f32_e32 v16, v16
	v_rcp_f32_e32 v17, v17
	v_rcp_f32_e32 v18, v18
	v_rcp_f32_e32 v19, v19
	v_mul_f32_e32 v16, v16, v22
	v_mul_f32_e32 v17, v17, v23
	v_mul_f32_e32 v18, v18, v24
	v_mul_f32_e32 v19, v19, v25
	v_cvt_pk_bf16_f32 v16, v16, v17
	v_cvt_pk_bf16_f32 v17, v18, v19
	global_store_dwordx2 v[32:33], v[16:17], off offset:288
	v_lshlrev_b64 v[16:17], 12, v[30:31]
	v_lshl_add_u64 v[16:17], s[18:19], 0, v[16:17]
	global_load_dwordx2 v[18:19], v[20:21], off offset:32
	s_waitcnt vmcnt(2)
	v_lshlrev_b32_e32 v26, 16, v34
	v_and_b32_e32 v27, 0xffff0000, v34
	v_lshl_add_u64 v[16:17], v[16:17], 0, v[142:143]
	v_lshlrev_b32_e32 v28, 16, v35
	v_and_b32_e32 v29, 0xffff0000, v35
	v_add_f32_e32 v12, v12, v232
	v_add_f32_e32 v13, v13, v233
	v_add_f32_e32 v14, v14, v234
	v_add_f32_e32 v15, v15, v235
	v_mul_f32_e32 v12, 0xbfb8aa3b, v12
	v_mul_f32_e32 v13, 0xbfb8aa3b, v13
	v_mul_f32_e32 v14, 0xbfb8aa3b, v14
	v_mul_f32_e32 v15, 0xbfb8aa3b, v15
	v_exp_f32_e32 v12, v12
	v_exp_f32_e32 v13, v13
	v_exp_f32_e32 v14, v14
	v_exp_f32_e32 v15, v15
	v_add_f32_e32 v12, 1.0, v12
	v_add_f32_e32 v13, 1.0, v13
	v_add_f32_e32 v14, 1.0, v14
	v_add_f32_e32 v15, 1.0, v15
	v_rcp_f32_e32 v12, v12
	v_rcp_f32_e32 v13, v13
	v_rcp_f32_e32 v14, v14
	v_rcp_f32_e32 v15, v15
	v_mul_f32_e32 v12, v12, v26
	v_mul_f32_e32 v13, v13, v27
	v_mul_f32_e32 v14, v14, v28
	v_mul_f32_e32 v15, v15, v29
	v_cvt_pk_bf16_f32 v12, v12, v13
	v_cvt_pk_bf16_f32 v13, v14, v15
	global_store_dwordx2 v[16:17], v[12:13], off
	s_waitcnt vmcnt(1)
	v_lshlrev_b32_e32 v22, 16, v18
	v_and_b32_e32 v23, 0xffff0000, v18
	v_lshlrev_b32_e32 v24, 16, v19
	v_and_b32_e32 v25, 0xffff0000, v19
	global_load_dwordx2 v[18:19], v[20:21], off offset:256
	v_add_f32_e32 v8, v8, v236
	v_add_f32_e32 v9, v9, v237
	v_add_f32_e32 v10, v10, v238
	v_add_f32_e32 v11, v11, v239
	v_mul_f32_e32 v8, 0xbfb8aa3b, v8
	v_mul_f32_e32 v9, 0xbfb8aa3b, v9
	v_mul_f32_e32 v10, 0xbfb8aa3b, v10
	v_mul_f32_e32 v11, 0xbfb8aa3b, v11
	v_exp_f32_e32 v8, v8
	v_exp_f32_e32 v9, v9
	v_exp_f32_e32 v10, v10
	v_exp_f32_e32 v11, v11
	v_add_f32_e32 v8, 1.0, v8
	v_add_f32_e32 v9, 1.0, v9
	v_add_f32_e32 v10, 1.0, v10
	v_add_f32_e32 v11, 1.0, v11
	v_rcp_f32_e32 v8, v8
	v_rcp_f32_e32 v9, v9
	v_rcp_f32_e32 v10, v10
	v_rcp_f32_e32 v11, v11
	v_mul_f32_e32 v8, v8, v22
	v_mul_f32_e32 v9, v9, v23
	v_mul_f32_e32 v10, v10, v24
	v_mul_f32_e32 v11, v11, v25
	v_cvt_pk_bf16_f32 v8, v8, v9
	v_cvt_pk_bf16_f32 v9, v10, v11
	global_store_dwordx2 v[16:17], v[8:9], off offset:32
	s_waitcnt vmcnt(1)
	v_add_f32_e32 v4, v4, v240
	v_add_f32_e32 v5, v5, v241
	v_add_f32_e32 v6, v6, v242
	v_add_f32_e32 v7, v7, v243
	v_mul_f32_e32 v4, 0xbfb8aa3b, v4
	v_mul_f32_e32 v5, 0xbfb8aa3b, v5
	v_mul_f32_e32 v6, 0xbfb8aa3b, v6
	v_mul_f32_e32 v7, 0xbfb8aa3b, v7
	v_exp_f32_e32 v4, v4
	v_exp_f32_e32 v5, v5
	v_exp_f32_e32 v6, v6
	v_exp_f32_e32 v7, v7
	v_add_f32_e32 v4, 1.0, v4
	v_add_f32_e32 v5, 1.0, v5
	v_add_f32_e32 v6, 1.0, v6
	v_add_f32_e32 v7, 1.0, v7
	v_rcp_f32_e32 v4, v4
	v_rcp_f32_e32 v5, v5
	v_rcp_f32_e32 v6, v6
	v_rcp_f32_e32 v7, v7
	global_load_dwordx2 v[8:9], v[20:21], off offset:288
	v_lshlrev_b32_e32 v14, 16, v18
	v_and_b32_e32 v15, 0xffff0000, v18
	v_lshlrev_b32_e32 v18, 16, v19
	v_and_b32_e32 v19, 0xffff0000, v19
	v_mul_f32_e32 v4, v4, v14
	v_mul_f32_e32 v5, v5, v15
	v_mul_f32_e32 v6, v6, v18
	v_mul_f32_e32 v7, v7, v19
	v_cvt_pk_bf16_f32 v4, v4, v5
	v_cvt_pk_bf16_f32 v5, v6, v7
	global_store_dwordx2 v[16:17], v[4:5], off offset:256
	s_waitcnt vmcnt(1)
	v_lshlrev_b32_e32 v10, 16, v8
	v_and_b32_e32 v8, 0xffff0000, v8
	v_lshlrev_b32_e32 v11, 16, v9
	v_and_b32_e32 v9, 0xffff0000, v9
	v_add_f32_e32 v0, v0, v244
	v_add_f32_e32 v1, v1, v245
	v_add_f32_e32 v2, v2, v246
	v_add_f32_e32 v3, v3, v247
	v_mul_f32_e32 v0, 0xbfb8aa3b, v0
	v_mul_f32_e32 v1, 0xbfb8aa3b, v1
	v_mul_f32_e32 v2, 0xbfb8aa3b, v2
	v_mul_f32_e32 v3, 0xbfb8aa3b, v3
	v_exp_f32_e32 v0, v0
	v_exp_f32_e32 v1, v1
	v_exp_f32_e32 v2, v2
	v_exp_f32_e32 v3, v3
	v_add_f32_e32 v0, 1.0, v0
	v_add_f32_e32 v1, 1.0, v1
	v_add_f32_e32 v2, 1.0, v2
	v_add_f32_e32 v3, 1.0, v3
	v_rcp_f32_e32 v0, v0
	v_rcp_f32_e32 v1, v1
	v_rcp_f32_e32 v2, v2
	v_rcp_f32_e32 v3, v3
	v_mul_f32_e32 v0, v0, v10
	v_mul_f32_e32 v1, v1, v8
	v_mul_f32_e32 v2, v2, v11
	v_mul_f32_e32 v3, v3, v9
	v_cvt_pk_bf16_f32 v0, v0, v1
	v_cvt_pk_bf16_f32 v1, v2, v3
	global_store_dwordx2 v[16:17], v[0:1], off offset:288
	s_cbranch_vccnz .LBB0_1324
	s_andn2_b64 vcc, exec, s[10:11]
	s_cbranch_vccnz .LBB0_1323
	s_barrier
	s_branch .LBB0_1323

.LBB0_1541:
	s_cmpk_lt_i32 s73, 0x2100
	v_mov_b32_e32 v0, v184
	s_cbranch_scc0 .LBB0_1544
	v_and_b32_e32 v1, 64, v198
	v_add_u32_e32 v1, 64, v1
	v_xor_b32_e32 v3, 1, v198
	v_cmp_lt_i32_e32 vcc, v3, v1
	s_movk_i32 s16, 0x5f
	s_mov_b64 s[66:67], s[54:55]
	v_cndmask_b32_e32 v3, v198, v3, vcc
	v_lshlrev_b32_e32 v80, 2, v3
	v_xor_b32_e32 v3, 2, v198
	v_cmp_lt_i32_e32 vcc, v3, v1
	v_lshlrev_b32_e32 v2, 3, v0
	v_add_u32_e32 v9, 0x6f, v0
	v_cndmask_b32_e32 v3, v198, v3, vcc
	v_lshlrev_b32_e32 v81, 2, v3
	v_xor_b32_e32 v3, 4, v198
	v_cmp_lt_i32_e32 vcc, v3, v1
	s_mov_b64 s[64:65], s[52:53]
	s_mov_b64 s[62:63], s[50:51]
	v_cndmask_b32_e32 v3, v198, v3, vcc
	v_lshlrev_b32_e32 v82, 2, v3
	v_xor_b32_e32 v3, 8, v198
	v_cmp_lt_i32_e32 vcc, v3, v1
	v_readlane_b32 s40, v252, 48
	s_lshl_b32 s38, s73, 1
	v_cndmask_b32_e32 v3, v198, v3, vcc
	v_lshlrev_b32_e32 v83, 2, v3
	v_xor_b32_e32 v3, 16, v198
	v_cmp_lt_i32_e32 vcc, v3, v1
	v_add_u32_e32 v4, 0x200, v2
	v_add_u32_e32 v6, 0x400, v2
	v_cndmask_b32_e32 v3, v198, v3, vcc
	v_lshlrev_b32_e32 v84, 2, v3
	v_xor_b32_e32 v3, 32, v198
	v_cmp_lt_i32_e32 vcc, v3, v1
	v_add_u32_e32 v8, 0xffffffb0, v0
	v_cmp_gt_u32_e64 s[6:7], s16, v9
	v_cndmask_b32_e32 v1, v198, v3, vcc
	v_lshlrev_b32_e32 v85, 2, v1
	v_add_u32_e32 v1, 47, v0
	v_cmp_gt_u32_e64 s[0:1], s16, v1
	v_subrev_u32_e32 v1, 48, v0
	v_cmp_gt_u32_e64 s[2:3], 48, v1
	v_add_u32_e32 v1, 0xffffffa0, v0
	v_cmp_gt_u32_e64 s[4:5], 48, v1
	v_add_u32_e32 v1, 0xffffff70, v0
	v_add_u32_e32 v9, 16, v0
	v_cmp_gt_u32_e64 s[14:15], 48, v1
	v_add_u32_e32 v1, 0xaf, v0
	v_readlane_b32 s42, v252, 50
	v_readlane_b32 s43, v252, 51
	v_readlane_b32 s46, v252, 54
	v_readlane_b32 s47, v252, 55
	v_ashrrev_i32_e32 v3, 31, v2
	v_ashrrev_i32_e32 v5, 31, v4
	v_ashrrev_i32_e32 v7, 31, v6
	v_cmp_gt_u32_e64 s[8:9], 48, v9
	v_subrev_u32_e32 v9, 32, v0
	v_cmp_gt_u32_e64 s[12:13], 48, v8
	v_add_u32_e32 v8, 0x50, v0
	v_cmp_gt_u32_e64 s[16:17], s16, v1
	v_add_u32_e32 v1, 32, v0
	v_add_u32_e32 v0, -16, v0
	s_mov_b64 s[42:43], s[46:47]
	s_ashr_i32 s39, s38, 31
	v_cmp_gt_u32_e64 s[10:11], 48, v9
	v_cmp_gt_u32_e64 s[18:19], 48, v8
	v_cmp_gt_u32_e64 s[20:21], 48, v1
	v_cmp_gt_u32_e64 s[22:23], 48, v0
	v_lshl_add_u64 v[8:9], v[2:3], 2, s[42:43]
	v_lshl_add_u64 v[10:11], v[6:7], 2, s[42:43]
	s_lshl_b64 s[24:25], s[38:39], 12
	v_lshlrev_b64 v[0:1], 1, v[2:3]
	v_lshlrev_b64 v[2:3], 1, v[4:5]
	v_lshlrev_b64 v[4:5], 1, v[6:7]
	v_mov_b32_e32 v6, 0x2600
	v_lshl_add_u64 v[12:13], s[24:25], 0, v[0:1]
	v_lshl_add_u64 v[14:15], s[24:25], 0, v[2:3]
	v_lshl_add_u64 v[16:17], s[24:25], 0, v[4:5]
	v_mad_i64_i32 v[20:21], s[24:25], s38, v6, v[2:3]
	v_mov_b32_e32 v2, 0xc00
	s_lshl_b32 s30, s94, 4
	v_readlane_b32 s52, v252, 60
	v_readlane_b32 s53, v252, 61
	v_readlane_b32 s54, v252, 62
	v_readlane_b32 s55, v252, 63
	v_mad_i64_i32 v[18:19], s[24:25], s38, v6, v[0:1]
	v_mad_i64_i32 v[22:23], s[24:25], s38, v6, v[4:5]
	v_mad_i64_i32 v[24:25], s[24:25], s38, v2, v[0:1]
	v_readlane_b32 s41, v252, 49
	v_readlane_b32 s44, v252, 52
	v_readlane_b32 s45, v252, 53
	v_readlane_b32 s50, v252, 58
	v_readlane_b32 s51, v252, 59
	s_mov_b64 s[52:53], s[64:65]
	s_ashr_i32 s31, s30, 31
	s_mov_b32 s24, 0x358637bd
	s_mov_b64 s[54:55], s[66:67]
	s_mov_b64 s[50:51], s[62:63]
	s_lshl_b64 s[40:41], s[30:31], 12
	s_mul_i32 s42, s94, 0x26000
	s_mul_hi_i32 s43, s30, 0x2600
	s_mul_i32 s44, s94, 0xc000
	s_mul_hi_i32 s45, s30, 0xc00
	s_mov_b32 s46, 0x3b2aaaab
	s_mov_b32 s31, 0x800000
	s_mov_b32 s33, 0xee94000
	s_mov_b32 s39, 0xee95000
	v_mov_b64_e32 v[26:27], s[24:25]
	v_readlane_b32 s48, v252, 56
	v_readlane_b32 s49, v252, 57
	global_load_dwordx4 v[200:203], v[8:9], off
	global_load_dwordx4 v[204:207], v[8:9], off offset:16
	global_load_dwordx4 v[208:211], v[8:9], off offset:2048
	global_load_dwordx4 v[212:215], v[8:9], off offset:2064
	global_load_dwordx4 v[216:219], v[10:11], off
	global_load_dwordx4 v[220:223], v[10:11], off offset:16
.LBB0_1543:
	v_lshl_add_u64 v[36:37], s[54:55], 0, v[24:25]
	v_add_co_u32_e32 v48, vcc, 0x14114000, v36
	v_lshl_add_u64 v[38:39], s[54:55], 0, v[18:19]
	s_nop 0
	v_addc_co_u32_e32 v49, vcc, 0, v37, vcc
	v_add_co_u32_e32 v62, vcc, 0x51d4000, v38
	v_lshl_add_u64 v[40:41], s[54:55], 0, v[20:21]
	s_nop 0
	v_addc_co_u32_e32 v63, vcc, 0, v39, vcc
	global_load_dwordx4 v[50:53], v[48:49], off offset:1024
	global_load_dwordx4 v[54:57], v[48:49], off
	global_load_dwordx4 v[58:61], v[48:49], off offset:2048
	global_load_dwordx4 v[86:89], v[48:49], off offset:3072
	v_add_co_u32_e32 v48, vcc, 0x51d4000, v40
	v_lshl_add_u64 v[42:43], s[54:55], 0, v[22:23]
	s_nop 0
	v_addc_co_u32_e32 v49, vcc, 0, v41, vcc
	global_load_dwordx4 v[90:93], v[62:63], off offset:1024
	global_load_dwordx4 v[94:97], v[48:49], off offset:1024
	v_add_co_u32_e32 v62, vcc, 0x51d4000, v42
	v_lshl_add_u64 v[46:47], s[54:55], 0, v[12:13]
	s_nop 0
	v_addc_co_u32_e32 v63, vcc, 0, v43, vcc
	v_add_co_u32_e32 v38, vcc, 0x51d6000, v38
	v_add_co_u32_e64 v44, s[24:25], s33, v46
	s_nop 0
	v_addc_co_u32_e32 v39, vcc, 0, v39, vcc
	v_add_co_u32_e32 v36, vcc, 0x14115000, v36
	global_load_dwordx4 v[98:101], v[62:63], off offset:1024
	global_load_dwordx4 v[102:105], v[38:39], off offset:2560
	v_addc_co_u32_e32 v37, vcc, 0, v37, vcc
	v_add_co_u32_e32 v38, vcc, 0x51d6000, v40
	global_load_dwordx4 v[106:109], v[36:37], off
	global_load_dwordx4 v[110:113], v[36:37], off offset:1024
	v_addc_co_u32_e32 v39, vcc, 0, v41, vcc
	v_add_co_u32_e32 v36, vcc, 0x51d6000, v42
	v_lshl_add_u64 v[30:31], s[54:55], 0, v[14:15]
	s_nop 0
	v_addc_co_u32_e32 v37, vcc, 0, v43, vcc
	global_load_dwordx4 v[114:117], v[38:39], off offset:2560
	global_load_dwordx4 v[118:121], v[36:37], off offset:2560
	v_addc_co_u32_e64 v45, s[24:25], 0, v47, s[24:25]
	v_add_co_u32_e64 v34, s[24:25], s33, v30
	v_lshl_add_u64 v[28:29], s[54:55], 0, v[16:17]
	s_nop 0
	v_addc_co_u32_e64 v35, s[24:25], 0, v31, s[24:25]
	v_add_co_u32_e64 v32, s[24:25], s33, v28
	s_add_i32 s38, s38, s30
	s_nop 0
	v_addc_co_u32_e64 v33, s[24:25], 0, v29, s[24:25]
	v_add_co_u32_e64 v46, s[24:25], s39, v46
	v_lshl_add_u64 v[12:13], v[12:13], 0, s[40:41]
	s_nop 0
	v_addc_co_u32_e64 v47, s[24:25], 0, v47, s[24:25]
	v_lshl_add_u64 v[14:15], v[14:15], 0, s[40:41]
	v_lshl_add_u64 v[16:17], v[16:17], 0, s[40:41]
	v_lshl_add_u64 v[18:19], v[18:19], 0, s[42:43]
	v_lshl_add_u64 v[20:21], v[20:21], 0, s[42:43]
	v_lshl_add_u64 v[22:23], v[22:23], 0, s[42:43]
	v_lshl_add_u64 v[24:25], v[24:25], 0, s[44:45]
	s_cmpk_lt_i32 s38, 0x4200
	s_waitcnt vmcnt(11)
	v_lshlrev_b32_e32 v65, 16, v50
	s_waitcnt vmcnt(10)
	v_lshlrev_b32_e32 v72, 16, v56
	v_and_b32_e32 v74, 0xffff0000, v56
	s_waitcnt vmcnt(8)
	v_lshlrev_b32_e32 v48, 16, v86
	v_and_b32_e32 v36, 0xffff0000, v86
	v_lshlrev_b32_e32 v56, 16, v88
	v_and_b32_e32 v40, 0xffff0000, v88
	v_lshlrev_b32_e32 v64, 16, v54
	v_and_b32_e32 v67, 0xffff0000, v50
	s_waitcnt vmcnt(7)
	v_lshlrev_b32_e32 v86, 16, v90
	v_and_b32_e32 v88, 0xffff0000, v90
	v_and_b32_e32 v122, 0xffff0000, v91
	v_and_b32_e32 v66, 0xffff0000, v54
	v_lshlrev_b32_e32 v69, 16, v51
	v_lshlrev_b32_e32 v68, 16, v55
	v_and_b32_e32 v71, 0xffff0000, v51
	v_and_b32_e32 v70, 0xffff0000, v55
	v_lshlrev_b32_e32 v73, 16, v52
	v_and_b32_e32 v75, 0xffff0000, v52
	v_lshlrev_b32_e32 v50, 16, v58
	v_and_b32_e32 v51, 0xffff0000, v58
	v_and_b32_e32 v54, 0xffff0000, v59
	v_lshlrev_b32_e32 v55, 16, v59
	v_and_b32_e32 v58, 0xffff0000, v60
	v_lshlrev_b32_e32 v59, 16, v60
	v_lshlrev_b32_e32 v52, 16, v87
	v_and_b32_e32 v38, 0xffff0000, v87
	v_lshlrev_b32_e32 v60, 16, v89
	v_and_b32_e32 v42, 0xffff0000, v89
	v_lshlrev_b32_e32 v90, 16, v91
	v_lshlrev_b32_e32 v124, 16, v92
	v_and_b32_e32 v92, 0xffff0000, v92
	v_lshlrev_b32_e32 v126, 16, v93
	v_and_b32_e32 v128, 0xffff0000, v93
	s_waitcnt vmcnt(6)
	v_lshlrev_b32_e32 v87, 16, v94
	v_and_b32_e32 v89, 0xffff0000, v94
	v_mul_f32_e32 v37, 0xbfb8aa3b, v86
	v_mul_f32_e32 v39, 0xbfb8aa3b, v88
	v_mul_f32_e32 v43, 0xbfb8aa3b, v122
	v_lshlrev_b32_e32 v77, 16, v53
	v_lshlrev_b32_e32 v76, 16, v57
	v_and_b32_e32 v79, 0xffff0000, v53
	v_and_b32_e32 v78, 0xffff0000, v57
	v_and_b32_e32 v62, 0xffff0000, v61
	v_lshlrev_b32_e32 v63, 16, v61
	v_lshlrev_b32_e32 v91, 16, v95
	v_mul_f32_e32 v41, 0xbfb8aa3b, v90
	v_and_b32_e32 v123, 0xffff0000, v95
	v_lshlrev_b32_e32 v125, 16, v96
	v_mul_f32_e32 v49, 0xbfb8aa3b, v124
	v_and_b32_e32 v93, 0xffff0000, v96
	v_mul_f32_e32 v53, 0xbfb8aa3b, v92
	v_lshlrev_b32_e32 v127, 16, v97
	v_mul_f32_e32 v57, 0xbfb8aa3b, v126
	v_and_b32_e32 v129, 0xffff0000, v97
	v_mul_f32_e32 v61, 0xbfb8aa3b, v128
	v_exp_f32_e32 v142, v37
	v_exp_f32_e32 v143, v39
	v_exp_f32_e32 v145, v43
	v_mul_f32_e32 v37, 0xbfb8aa3b, v87
	v_mul_f32_e32 v39, 0xbfb8aa3b, v89
	s_waitcnt vmcnt(5)
	v_lshlrev_b32_e32 v94, 16, v98
	v_and_b32_e32 v95, 0xffff0000, v98
	v_exp_f32_e32 v144, v41
	v_exp_f32_e32 v146, v49
	v_exp_f32_e32 v147, v53
	v_exp_f32_e32 v148, v57
	v_exp_f32_e32 v149, v61
	v_mul_f32_e32 v41, 0xbfb8aa3b, v91
	v_mul_f32_e32 v43, 0xbfb8aa3b, v123
	v_mul_f32_e32 v49, 0xbfb8aa3b, v125
	v_mul_f32_e32 v53, 0xbfb8aa3b, v93
	v_mul_f32_e32 v57, 0xbfb8aa3b, v127
	v_mul_f32_e32 v61, 0xbfb8aa3b, v129
	v_and_b32_e32 v96, 0xffff0000, v99
	v_lshlrev_b32_e32 v97, 16, v99
	v_and_b32_e32 v98, 0xffff0000, v100
	v_lshlrev_b32_e32 v99, 16, v100
	v_exp_f32_e32 v151, v37
	v_exp_f32_e32 v153, v39
	v_mul_f32_e32 v37, 0xbfb8aa3b, v94
	v_mul_f32_e32 v39, 0xbfb8aa3b, v95
	v_and_b32_e32 v100, 0xffff0000, v101
	v_exp_f32_e32 v155, v41
	v_exp_f32_e32 v157, v43
	v_exp_f32_e32 v158, v49
	v_exp_f32_e32 v159, v53
	v_exp_f32_e32 v160, v57
	v_exp_f32_e32 v161, v61
	v_mul_f32_e32 v41, 0xbfb8aa3b, v97
	v_mul_f32_e32 v43, 0xbfb8aa3b, v96
	v_mul_f32_e32 v49, 0xbfb8aa3b, v99
	v_mul_f32_e32 v53, 0xbfb8aa3b, v98
	s_waitcnt vmcnt(4)
	v_lshlrev_b32_e32 v130, 16, v102
	v_and_b32_e32 v102, 0xffff0000, v102
	v_lshlrev_b32_e32 v132, 16, v103
	v_exp_f32_e32 v162, v37
	v_exp_f32_e32 v163, v39
	v_lshlrev_b32_e32 v101, 16, v101
	v_mul_f32_e32 v61, 0xbfb8aa3b, v100
	v_and_b32_e32 v134, 0xffff0000, v103
	v_lshlrev_b32_e32 v136, 16, v104
	v_and_b32_e32 v104, 0xffff0000, v104
	v_lshlrev_b32_e32 v138, 16, v105
	v_and_b32_e32 v140, 0xffff0000, v105
	v_exp_f32_e32 v164, v41
	v_exp_f32_e32 v165, v43
	v_exp_f32_e32 v166, v49
	v_exp_f32_e32 v167, v53
	v_mul_f32_e32 v133, 0xbfb8aa3b, v102
	v_mul_f32_e32 v135, 0xbfb8aa3b, v132
	v_mul_f32_e32 v57, 0xbfb8aa3b, v101
	v_exp_f32_e32 v169, v61
	v_mul_f32_e32 v105, 0xbfb8aa3b, v130
	v_mul_f32_e32 v137, 0xbfb8aa3b, v134
	v_mul_f32_e32 v139, 0xbfb8aa3b, v136
	v_mul_f32_e32 v141, 0xbfb8aa3b, v104
	v_mul_f32_e32 v150, 0xbfb8aa3b, v138
	v_mul_f32_e32 v152, 0xbfb8aa3b, v140
	s_waitcnt vmcnt(1)
	v_lshlrev_b32_e32 v131, 16, v114
	v_and_b32_e32 v103, 0xffff0000, v114
	v_exp_f32_e32 v171, v133
	v_lshlrev_b32_e32 v133, 16, v115
	v_exp_f32_e32 v172, v135
	v_and_b32_e32 v135, 0xffff0000, v115
	v_add_f32_e32 v143, 1.0, v143
	v_add_f32_e32 v145, 1.0, v145
	v_exp_f32_e32 v168, v57
	v_exp_f32_e32 v170, v105
	v_exp_f32_e32 v173, v137
	v_lshlrev_b32_e32 v137, 16, v116
	v_exp_f32_e32 v174, v139
	v_and_b32_e32 v105, 0xffff0000, v116
	v_exp_f32_e32 v175, v141
	v_lshlrev_b32_e32 v139, 16, v117
	v_exp_f32_e32 v176, v150
	v_and_b32_e32 v141, 0xffff0000, v117
	v_exp_f32_e32 v177, v152
	v_add_f32_e32 v142, 1.0, v142
	v_add_f32_e32 v150, 1.0, v144
	v_add_f32_e32 v152, 1.0, v146
	v_add_f32_e32 v147, 1.0, v147
	v_add_f32_e32 v154, 1.0, v148
	v_add_f32_e32 v149, 1.0, v149
	v_mul_f32_e32 v178, 0xbfb8aa3b, v131
	v_mul_f32_e32 v179, 0xbfb8aa3b, v103
	v_mul_f32_e32 v180, 0xbfb8aa3b, v133
	v_mul_f32_e32 v181, 0xbfb8aa3b, v135
	s_waitcnt vmcnt(0)
	v_lshlrev_b32_e32 v114, 16, v118
	v_and_b32_e32 v115, 0xffff0000, v118
	v_and_b32_e32 v116, 0xffff0000, v119
	v_lshlrev_b32_e32 v117, 16, v119
	v_and_b32_e32 v118, 0xffff0000, v120
	v_lshlrev_b32_e32 v119, 16, v120
	v_rcp_f32_e32 v144, v143
	v_rcp_f32_e32 v148, v145
	v_add_f32_e32 v143, 1.0, v151
	v_add_f32_e32 v145, 1.0, v153
	v_mul_f32_e32 v183, 0xbfb8aa3b, v105
	v_mul_f32_e32 v187, 0xbfb8aa3b, v141
	v_rcp_f32_e32 v142, v142
	v_rcp_f32_e32 v146, v150
	v_rcp_f32_e32 v150, v152
	v_rcp_f32_e32 v152, v147
	v_rcp_f32_e32 v156, v149
	v_add_f32_e32 v147, 1.0, v155
	v_add_f32_e32 v149, 1.0, v157
	v_add_f32_e32 v151, 1.0, v158
	v_add_f32_e32 v153, 1.0, v159
	v_add_f32_e32 v155, 1.0, v160
	v_add_f32_e32 v157, 1.0, v161
	v_exp_f32_e32 v188, v178
	v_exp_f32_e32 v179, v179
	v_exp_f32_e32 v189, v180
	v_exp_f32_e32 v181, v181
	v_mul_f32_e32 v158, 0xbfb8aa3b, v114
	v_mul_f32_e32 v159, 0xbfb8aa3b, v115
	v_mul_f32_e32 v160, 0xbfb8aa3b, v117
	v_mul_f32_e32 v161, 0xbfb8aa3b, v116
	v_mul_f32_e32 v178, 0xbfb8aa3b, v119
	v_mul_f32_e32 v180, 0xbfb8aa3b, v118
	v_rcp_f32_e32 v143, v143
	v_rcp_f32_e32 v145, v145
	v_add_f32_e32 v162, 1.0, v162
	v_add_f32_e32 v163, 1.0, v163
	v_and_b32_e32 v120, 0xffff0000, v121
	v_lshlrev_b32_e32 v121, 16, v121
	v_exp_f32_e32 v183, v183
	v_exp_f32_e32 v187, v187
	v_rcp_f32_e32 v147, v147
	v_rcp_f32_e32 v149, v149
	v_add_f32_e32 v164, 1.0, v164
	v_add_f32_e32 v165, 1.0, v165
	v_add_f32_e32 v166, 1.0, v166
	v_add_f32_e32 v167, 1.0, v167
	v_exp_f32_e32 v192, v158
	v_exp_f32_e32 v193, v159
	v_exp_f32_e32 v194, v160
	v_exp_f32_e32 v195, v161
	v_exp_f32_e32 v196, v178
	v_exp_f32_e32 v197, v180
	v_rcp_f32_e32 v158, v162
	v_rcp_f32_e32 v159, v163
	v_mul_f32_e32 v190, 0xbfb8aa3b, v121
	v_mul_f32_e32 v191, 0xbfb8aa3b, v120
	v_add_f32_e32 v169, 1.0, v169
	v_rcp_f32_e32 v161, v164
	v_rcp_f32_e32 v160, v165
	v_rcp_f32_e32 v163, v166
	v_rcp_f32_e32 v162, v167
	v_rcp_f32_e32 v153, v153
	v_add_f32_e32 v168, 1.0, v168
	v_exp_f32_e32 v190, v190
	v_exp_f32_e32 v191, v191
	v_rcp_f32_e32 v164, v169
	v_add_f32_e32 v167, 1.0, v171
	v_add_f32_e32 v169, 1.0, v172
	v_add_f32_e32 v171, 1.0, v173
	v_add_f32_e32 v173, 1.0, v174
	v_mul_f32_e32 v182, 0xbfb8aa3b, v137
	v_rcp_f32_e32 v151, v151
	v_rcp_f32_e32 v165, v168
	v_add_f32_e32 v166, 1.0, v170
	v_add_f32_e32 v177, 1.0, v177
	v_rcp_f32_e32 v168, v167
	v_rcp_f32_e32 v170, v169
	v_rcp_f32_e32 v174, v173
	v_add_f32_e32 v167, 1.0, v188
	v_add_f32_e32 v169, 1.0, v179
	v_add_f32_e32 v173, 1.0, v181
	v_pk_mul_f32 v[86:87], v[142:143], v[86:87]
	v_pk_mul_f32 v[88:89], v[144:145], v[88:89]
	v_exp_f32_e32 v182, v182
	v_add_f32_e32 v175, 1.0, v175
	v_rcp_f32_e32 v166, v166
	v_rcp_f32_e32 v172, v171
	v_rcp_f32_e32 v180, v177
	v_add_f32_e32 v171, 1.0, v189
	v_add_f32_e32 v177, 1.0, v183
	v_add_f32_e32 v181, 1.0, v187
	v_pk_mul_f32 v[90:91], v[146:147], v[90:91]
	v_pk_mul_f32 v[122:123], v[148:149], v[122:123]
	v_rcp_f32_e32 v167, v167
	v_rcp_f32_e32 v169, v169
	v_rcp_f32_e32 v173, v173
	v_add_f32_e32 v142, 1.0, v192
	v_add_f32_e32 v143, 1.0, v193
	v_add_f32_e32 v144, 1.0, v194
	v_add_f32_e32 v145, 1.0, v195
	v_add_f32_e32 v146, 1.0, v196
	v_add_f32_e32 v147, 1.0, v197
	v_pk_mul_f32 v[64:65], v[86:87], v[64:65]
	v_pk_mul_f32 v[66:67], v[88:89], v[66:67]
	v_pk_mul_f32 v[86:87], v[158:159], v[94:95]
	v_rcp_f32_e32 v154, v154
	v_rcp_f32_e32 v155, v155
	v_add_f32_e32 v178, 1.0, v176
	v_rcp_f32_e32 v176, v175
	v_rcp_f32_e32 v171, v171
	v_rcp_f32_e32 v177, v177
	v_rcp_f32_e32 v181, v181
	v_pk_mul_f32 v[68:69], v[90:91], v[68:69]
	v_pk_mul_f32 v[70:71], v[122:123], v[70:71]
	v_pk_mul_f32 v[88:89], v[160:161], v[96:97]
	v_pk_mul_f32 v[90:91], v[162:163], v[98:99]
	v_rcp_f32_e32 v94, v142
	v_rcp_f32_e32 v95, v143
	v_rcp_f32_e32 v97, v144
	v_rcp_f32_e32 v96, v145
	v_rcp_f32_e32 v99, v146
	v_rcp_f32_e32 v98, v147
	v_pk_mul_f32 v[122:123], v[66:67], v[66:67]
	v_pk_mul_f32 v[86:87], v[86:87], v[50:51]
	v_rcp_f32_e32 v157, v157
	v_pk_mul_f32 v[92:93], v[152:153], v[92:93]
	v_add_f32_e32 v148, 1.0, v190
	v_add_f32_e32 v149, 1.0, v191
	v_pk_mul_f32 v[88:89], v[88:89], v[54:55]
	v_pk_fma_f32 v[50:51], v[64:65], v[64:65], v[122:123]
	v_pk_mul_f32 v[54:55], v[86:87], v[86:87]
	v_pk_mul_f32 v[124:125], v[150:151], v[124:125]
	v_pk_mul_f32 v[74:75], v[92:93], v[74:75]
	v_pk_mul_f32 v[92:93], v[164:165], v[100:101]
	v_rcp_f32_e32 v101, v148
	v_rcp_f32_e32 v100, v149
	v_pk_mul_f32 v[122:123], v[88:89], v[88:89]
	v_pk_fma_f32 v[50:51], v[68:69], v[68:69], v[50:51]
	v_add_f32_e32 v142, v54, v55
	v_lshlrev_b32_e32 v49, 16, v106
	v_and_b32_e32 v37, 0xffff0000, v106
	v_and_b32_e32 v39, 0xffff0000, v107
	v_add_f32_e32 v175, 1.0, v182
	v_pk_mul_f32 v[72:73], v[124:125], v[72:73]
	v_pk_mul_f32 v[90:91], v[90:91], v[58:59]
	v_pk_mul_f32 v[54:55], v[166:167], v[130:131]
	v_pk_mul_f32 v[58:59], v[168:169], v[102:103]
	v_pk_mul_f32 v[102:103], v[172:173], v[134:135]
	v_pk_fma_f32 v[134:135], v[70:71], v[70:71], v[50:51]
	v_add_f32_e32 v123, v123, v142
	v_lshlrev_b32_e32 v53, 16, v107
	v_lshlrev_b32_e32 v57, 16, v108
	v_and_b32_e32 v41, 0xffff0000, v108
	v_lshlrev_b32_e32 v61, 16, v109
	v_and_b32_e32 v43, 0xffff0000, v109
	v_lshlrev_b32_e32 v106, 16, v110
	v_and_b32_e32 v107, 0xffff0000, v110
	v_and_b32_e32 v108, 0xffff0000, v111
	v_lshlrev_b32_e32 v109, 16, v111
	v_and_b32_e32 v110, 0xffff0000, v112
	v_lshlrev_b32_e32 v111, 16, v112
	v_pk_mul_f32 v[126:127], v[154:155], v[126:127]
	v_rcp_f32_e32 v175, v175
	v_pk_mul_f32 v[92:93], v[92:93], v[62:63]
	v_pk_mul_f32 v[124:125], v[90:91], v[90:91]
	v_pk_mul_f32 v[62:63], v[170:171], v[132:133]
	v_pk_mul_f32 v[104:105], v[176:177], v[104:105]
	v_pk_mul_f32 v[132:133], v[180:181], v[140:141]
	v_pk_mul_f32 v[48:49], v[54:55], v[48:49]
	v_pk_mul_f32 v[50:51], v[58:59], v[36:37]
	v_pk_mul_f32 v[54:55], v[102:103], v[38:39]
	v_pk_mul_f32 v[36:37], v[94:95], v[114:115]
	v_pk_mul_f32 v[38:39], v[96:97], v[116:117]
	v_pk_mul_f32 v[94:95], v[98:99], v[118:119]
	v_pk_fma_f32 v[98:99], v[72:73], v[72:73], v[134:135]
	v_add_f32_e32 v102, v122, v123
	v_pk_mul_f32 v[128:129], v[156:157], v[128:129]
	v_pk_mul_f32 v[76:77], v[126:127], v[76:77]
	v_pk_mul_f32 v[52:53], v[62:63], v[52:53]
	v_pk_mul_f32 v[58:59], v[104:105], v[40:41]
	v_pk_mul_f32 v[62:63], v[132:133], v[42:43]
	v_pk_mul_f32 v[42:43], v[36:37], v[106:107]
	v_pk_mul_f32 v[40:41], v[38:39], v[108:109]
	v_pk_mul_f32 v[38:39], v[94:95], v[110:111]
	v_pk_fma_f32 v[94:95], v[74:75], v[74:75], v[98:99]
	v_add_f32_e32 v106, v125, v102
	v_and_b32_e32 v112, 0xffff0000, v113
	v_lshlrev_b32_e32 v113, 16, v113
	v_pk_mul_f32 v[78:79], v[128:129], v[78:79]
	v_pk_mul_f32 v[126:127], v[92:93], v[92:93]
	v_pk_mul_f32 v[96:97], v[100:101], v[120:121]
	v_pk_mul_f32 v[100:101], v[50:51], v[50:51]
	v_pk_mul_f32 v[98:99], v[42:43], v[42:43]
	v_pk_fma_f32 v[94:95], v[76:77], v[76:77], v[94:95]
	v_add_f32_e32 v106, v124, v106
	v_pk_mul_f32 v[36:37], v[96:97], v[112:113]
	v_pk_fma_f32 v[96:97], v[48:49], v[48:49], v[100:101]
	v_pk_mul_f32 v[100:101], v[40:41], v[40:41]
	v_add_f32_e32 v98, v98, v99
	v_pk_fma_f32 v[94:95], v[78:79], v[78:79], v[94:95]
	v_add_f32_e32 v112, v127, v106
	v_pk_mul_f32 v[128:129], v[174:175], v[136:137]
	v_pk_fma_f32 v[96:97], v[52:53], v[52:53], v[96:97]
	v_add_f32_e32 v101, v101, v98
	v_cndmask_b32_e64 v99, 0, v94, s[4:5]
	v_cndmask_b32_e64 v107, 0, v95, s[10:11]
	v_cndmask_b32_e64 v106, 0, v95, s[12:13]
	v_cndmask_b32_e64 v98, 0, v94, s[14:15]
	v_add_f32_e32 v112, v126, v112
	v_pk_mul_f32 v[56:57], v[128:129], v[56:57]
	v_pk_mul_f32 v[102:103], v[38:39], v[38:39]
	v_pk_fma_f32 v[96:97], v[54:55], v[54:55], v[96:97]
	v_cndmask_b32_e64 v109, 0, v94, s[0:1]
	v_cndmask_b32_e64 v108, 0, v94, s[2:3]
	v_cndmask_b32_e64 v111, 0, v95, s[6:7]
	v_cndmask_b32_e64 v110, 0, v95, s[8:9]
	v_add_f32_e32 v113, v100, v101
	v_pk_add_f32 v[98:99], v[98:99], v[106:107]
	v_cndmask_b32_e64 v107, 0, v112, s[20:21]
	v_cndmask_b32_e64 v106, 0, v112, s[22:23]
	v_pk_fma_f32 v[94:95], v[56:57], v[56:57], v[96:97]
	v_pk_add_f32 v[96:97], v[108:109], v[110:111]
	v_cndmask_b32_e64 v101, 0, v112, s[16:17]
	v_cndmask_b32_e64 v100, 0, v112, s[18:19]
	v_add_f32_e32 v103, v103, v113
	v_pk_add_f32 v[98:99], v[98:99], v[106:107]
	v_pk_add_f32 v[96:97], v[96:97], v[100:101]
	v_add_f32_e32 v106, v102, v103
	ds_bpermute_b32 v103, v80, v99
	ds_bpermute_b32 v102, v80, v98
	ds_bpermute_b32 v101, v80, v97
	ds_bpermute_b32 v100, v80, v96
	v_mul_f32_e32 v186, 0xbfb8aa3b, v139
	v_exp_f32_e32 v186, v186
	s_waitcnt lgkmcnt(2)
	v_pk_add_f32 v[98:99], v[98:99], v[102:103]
	ds_bpermute_b32 v103, v81, v99
	s_waitcnt lgkmcnt(1)
	v_pk_add_f32 v[96:97], v[96:97], v[100:101]
	ds_bpermute_b32 v102, v81, v98
	ds_bpermute_b32 v101, v81, v97
	ds_bpermute_b32 v100, v81, v96
	v_add_f32_e32 v179, 1.0, v186
	v_rcp_f32_e32 v178, v178
	s_waitcnt lgkmcnt(2)
	v_pk_add_f32 v[98:99], v[98:99], v[102:103]
	ds_bpermute_b32 v103, v82, v99
	s_waitcnt lgkmcnt(1)
	v_pk_add_f32 v[96:97], v[96:97], v[100:101]
	ds_bpermute_b32 v102, v82, v98
	ds_bpermute_b32 v101, v82, v97
	ds_bpermute_b32 v100, v82, v96
	v_rcp_f32_e32 v179, v179
	v_pk_fma_f32 v[94:95], v[58:59], v[58:59], v[94:95]
	s_waitcnt lgkmcnt(2)
	v_pk_add_f32 v[98:99], v[98:99], v[102:103]
	ds_bpermute_b32 v103, v83, v99
	s_waitcnt lgkmcnt(1)
	v_pk_add_f32 v[96:97], v[96:97], v[100:101]
	ds_bpermute_b32 v102, v83, v98
	ds_bpermute_b32 v101, v83, v97
	ds_bpermute_b32 v100, v83, v96
	v_pk_mul_f32 v[130:131], v[178:179], v[138:139]
	v_pk_mul_f32 v[104:105], v[36:37], v[36:37]
	s_waitcnt lgkmcnt(2)
	v_pk_add_f32 v[98:99], v[98:99], v[102:103]
	ds_bpermute_b32 v103, v84, v99
	s_waitcnt lgkmcnt(1)
	v_pk_add_f32 v[96:97], v[96:97], v[100:101]
	ds_bpermute_b32 v102, v84, v98
	ds_bpermute_b32 v101, v84, v97
	ds_bpermute_b32 v100, v84, v96
	v_pk_mul_f32 v[60:61], v[130:131], v[60:61]
	v_add_f32_e32 v105, v105, v106
	s_waitcnt lgkmcnt(2)
	v_pk_add_f32 v[98:99], v[98:99], v[102:103]
	ds_bpermute_b32 v103, v85, v99
	s_waitcnt lgkmcnt(1)
	v_pk_add_f32 v[96:97], v[96:97], v[100:101]
	ds_bpermute_b32 v102, v85, v98
	ds_bpermute_b32 v101, v85, v97
	ds_bpermute_b32 v100, v85, v96
	v_pk_fma_f32 v[94:95], v[60:61], v[60:61], v[94:95]
	v_add_f32_e32 v104, v104, v105
	s_waitcnt lgkmcnt(2)
	v_pk_add_f32 v[98:99], v[98:99], v[102:103]
	v_pk_fma_f32 v[94:95], v[62:63], v[62:63], v[94:95]
	s_waitcnt lgkmcnt(0)
	v_pk_add_f32 v[96:97], v[96:97], v[100:101]
	v_pk_fma_f32 v[98:99], v[98:99], s[46:47], v[26:27] op_sel_hi:[1,0,0]
	v_pk_fma_f32 v[96:97], v[96:97], s[46:47], v[26:27] op_sel_hi:[1,0,0]
	v_mul_f32_e32 v102, 0x4b800000, v99
	v_mul_f32_e32 v103, 0x4b800000, v98
	v_cmp_gt_f32_e64 s[24:25], s31, v98
	v_cmp_gt_f32_e64 s[26:27], s31, v99
	v_mul_f32_e32 v101, 0x4b800000, v96
	v_cmp_gt_f32_e32 vcc, s31, v96
	v_cndmask_b32_e64 v99, v99, v102, s[26:27]
	v_cndmask_b32_e64 v98, v98, v103, s[24:25]
	v_mul_f32_e32 v100, 0x4b800000, v97
	v_cmp_gt_f32_e64 s[28:29], s31, v97
	v_cndmask_b32_e32 v96, v96, v101, vcc
	v_rsq_f32_e32 v99, v99
	v_rsq_f32_e32 v98, v98
	v_cndmask_b32_e64 v97, v97, v100, s[28:29]
	v_rsq_f32_e32 v96, v96
	v_rsq_f32_e32 v97, v97
	v_mul_f32_e32 v102, 0x45800000, v99
	v_mul_f32_e32 v103, 0x45800000, v98
	v_mul_f32_e32 v101, 0x45800000, v96
	v_cndmask_b32_e64 v102, v99, v102, s[26:27]
	v_cndmask_b32_e64 v103, v98, v103, s[24:25]
	v_mul_f32_e32 v100, 0x45800000, v97
	v_cndmask_b32_e32 v101, v96, v101, vcc
	v_cndmask_b32_e64 v96, v103, v102, s[4:5]
	v_cndmask_b32_e64 v100, v97, v100, s[28:29]
	v_cndmask_b32_e64 v96, v96, v101, s[2:3]
	v_cndmask_b32_e64 v96, v96, v100, s[0:1]
	v_mul_f32_e32 v78, v78, v96
	v_mul_f32_e32 v64, v64, v96
	v_mul_f32_e32 v66, v66, v96
	v_mul_f32_e32 v68, v68, v96
	v_mul_f32_e32 v70, v70, v96
	v_mul_f32_e32 v72, v72, v96
	v_mul_f32_e32 v74, v74, v96
	v_mul_f32_e32 v76, v76, v96
	v_mul_f32_e32 v3, v207, v78
	v_mul_f32_e32 v4, v200, v64
	v_mul_f32_e32 v5, v201, v66
	v_mul_f32_e32 v6, v202, v68
	v_mul_f32_e32 v7, v203, v70
	v_mul_f32_e32 v64, v204, v72
	v_mul_f32_e32 v66, v205, v74
	v_mul_f32_e32 v68, v206, v76
	v_cvt_pk_bf16_f32 v0, v4, v5
	v_cvt_pk_bf16_f32 v1, v6, v7
	v_cvt_pk_bf16_f32 v2, v64, v66
	v_cvt_pk_bf16_f32 v3, v68, v3
	global_store_dwordx4 v[44:45], v[0:3], off offset:1024
	v_cndmask_b32_e64 v64, v103, v102, s[10:11]
	v_cndmask_b32_e64 v64, v64, v101, s[8:9]
	v_cndmask_b32_e64 v64, v64, v100, s[6:7]
	v_mul_f32_e32 v65, v65, v64
	v_mul_f32_e32 v66, v67, v64
	v_mul_f32_e32 v67, v69, v64
	v_mul_f32_e32 v68, v71, v64
	v_mul_f32_e32 v69, v73, v64
	v_mul_f32_e32 v70, v75, v64
	v_mul_f32_e32 v71, v77, v64
	v_mul_f32_e32 v64, v79, v64
	v_cndmask_b32_e64 v107, 0, v94, s[4:5]
	v_cndmask_b32_e64 v109, 0, v95, s[10:11]
	v_cndmask_b32_e64 v108, 0, v95, s[12:13]
	v_cndmask_b32_e64 v106, 0, v94, s[14:15]
	v_cndmask_b32_e64 v111, 0, v94, s[0:1]
	v_cndmask_b32_e64 v110, 0, v94, s[2:3]
	v_cndmask_b32_e64 v113, 0, v95, s[6:7]
	v_cndmask_b32_e64 v112, 0, v95, s[8:9]
	v_pk_add_f32 v[94:95], v[110:111], v[112:113]
	v_cndmask_b32_e64 v45, 0, v104, s[16:17]
	v_cndmask_b32_e64 v44, 0, v104, s[18:19]
	v_pk_add_f32 v[96:97], v[106:107], v[108:109]
	v_cndmask_b32_e64 v99, 0, v104, s[20:21]
	v_cndmask_b32_e64 v98, 0, v104, s[22:23]
	v_pk_add_f32 v[44:45], v[94:95], v[44:45]
	v_pk_add_f32 v[94:95], v[96:97], v[98:99]
	ds_bpermute_b32 v99, v80, v95
	ds_bpermute_b32 v98, v80, v94
	ds_bpermute_b32 v97, v80, v45
	ds_bpermute_b32 v96, v80, v44
	s_waitcnt lgkmcnt(2)
	v_pk_add_f32 v[94:95], v[94:95], v[98:99]
	s_waitcnt lgkmcnt(0)
	v_pk_add_f32 v[44:45], v[44:45], v[96:97]
	ds_bpermute_b32 v97, v81, v45
	ds_bpermute_b32 v96, v81, v44
	s_waitcnt lgkmcnt(0)
	v_pk_add_f32 v[44:45], v[44:45], v[96:97]
	v_mul_f32_e32 v0, v208, v65
	v_mul_f32_e32 v1, v209, v66
	v_mul_f32_e32 v2, v210, v67
	v_mul_f32_e32 v3, v211, v68
	v_mul_f32_e32 v4, v212, v69
	v_mul_f32_e32 v5, v213, v70
	v_mul_f32_e32 v6, v214, v71
	v_mul_f32_e32 v7, v215, v64
	v_cvt_pk_bf16_f32 v0, v0, v1
	v_cvt_pk_bf16_f32 v1, v2, v3
	v_cvt_pk_bf16_f32 v2, v4, v5
	v_cvt_pk_bf16_f32 v3, v6, v7
	global_store_dwordx4 v[34:35], v[0:3], off offset:1024
	ds_bpermute_b32 v35, v81, v95
	ds_bpermute_b32 v34, v81, v94
	ds_bpermute_b32 v65, v82, v45
	ds_bpermute_b32 v64, v82, v44
	s_waitcnt lgkmcnt(2)
	v_pk_add_f32 v[34:35], v[94:95], v[34:35]
	ds_bpermute_b32 v67, v82, v35
	ds_bpermute_b32 v66, v82, v34
	s_waitcnt lgkmcnt(2)
	v_pk_add_f32 v[44:45], v[44:45], v[64:65]
	ds_bpermute_b32 v65, v83, v45
	ds_bpermute_b32 v64, v83, v44
	s_waitcnt lgkmcnt(2)
	v_pk_add_f32 v[34:35], v[34:35], v[66:67]
	ds_bpermute_b32 v67, v83, v35
	ds_bpermute_b32 v66, v83, v34
	s_waitcnt lgkmcnt(2)
	v_pk_add_f32 v[44:45], v[44:45], v[64:65]
	ds_bpermute_b32 v65, v84, v45
	ds_bpermute_b32 v64, v84, v44
	s_waitcnt lgkmcnt(2)
	v_pk_add_f32 v[34:35], v[34:35], v[66:67]
	v_cndmask_b32_e64 v66, v103, v102, s[20:21]
	v_cndmask_b32_e64 v66, v66, v101, s[18:19]
	v_cndmask_b32_e64 v66, v66, v100, s[16:17]
	v_mul_f32_e32 v68, v86, v66
	v_mul_f32_e32 v69, v87, v66
	v_mul_f32_e32 v70, v89, v66
	v_mul_f32_e32 v71, v88, v66
	v_mul_f32_e32 v72, v91, v66
	v_mul_f32_e32 v73, v90, v66
	v_mul_f32_e32 v74, v93, v66
	v_mul_f32_e32 v66, v92, v66
	ds_bpermute_b32 v67, v84, v35
	v_mul_f32_e32 v0, v68, v216
	v_mul_f32_e32 v1, v69, v217
	v_mul_f32_e32 v2, v70, v218
	v_mul_f32_e32 v3, v71, v219
	v_mul_f32_e32 v4, v72, v220
	v_mul_f32_e32 v5, v73, v221
	v_mul_f32_e32 v6, v74, v222
	v_mul_f32_e32 v7, v66, v223
	v_cvt_pk_bf16_f32 v0, v0, v1
	v_cvt_pk_bf16_f32 v1, v2, v3
	v_cvt_pk_bf16_f32 v2, v4, v5
	v_cvt_pk_bf16_f32 v3, v6, v7
	global_store_dwordx4 v[32:33], v[0:3], off offset:1024
	ds_bpermute_b32 v66, v84, v34
	s_waitcnt lgkmcnt(2)
	v_pk_add_f32 v[32:33], v[44:45], v[64:65]
	ds_bpermute_b32 v45, v85, v33
	ds_bpermute_b32 v44, v85, v32
	s_waitcnt lgkmcnt(2)
	v_pk_add_f32 v[34:35], v[34:35], v[66:67]
	ds_bpermute_b32 v65, v85, v35
	ds_bpermute_b32 v64, v85, v34
	s_waitcnt lgkmcnt(2)
	v_pk_add_f32 v[32:33], v[32:33], v[44:45]
	s_waitcnt lgkmcnt(0)
	v_pk_add_f32 v[34:35], v[34:35], v[64:65]
	s_nop 0
	v_pk_fma_f32 v[34:35], v[34:35], s[46:47], v[26:27] op_sel_hi:[1,0,0]
	v_pk_fma_f32 v[32:33], v[32:33], s[46:47], v[26:27] op_sel_hi:[1,0,0]
	v_mul_f32_e32 v64, 0x4b800000, v35
	v_mul_f32_e32 v65, 0x4b800000, v34
	v_cmp_gt_f32_e64 s[24:25], s31, v34
	v_cmp_gt_f32_e64 s[26:27], s31, v35
	v_mul_f32_e32 v44, 0x4b800000, v33
	v_mul_f32_e32 v45, 0x4b800000, v32
	v_cmp_gt_f32_e32 vcc, s31, v32
	v_cmp_gt_f32_e64 s[28:29], s31, v33
	v_cndmask_b32_e64 v35, v35, v64, s[26:27]
	v_cndmask_b32_e64 v34, v34, v65, s[24:25]
	v_cndmask_b32_e64 v33, v33, v44, s[28:29]
	v_cndmask_b32_e32 v32, v32, v45, vcc
	v_rsq_f32_e32 v35, v35
	v_rsq_f32_e32 v34, v34
	v_rsq_f32_e32 v33, v33
	v_rsq_f32_e32 v32, v32
	v_mul_f32_e32 v64, 0x45800000, v35
	v_mul_f32_e32 v65, 0x45800000, v34
	v_mul_f32_e32 v44, 0x45800000, v33
	v_mul_f32_e32 v45, 0x45800000, v32
	v_cndmask_b32_e64 v35, v35, v64, s[26:27]
	v_cndmask_b32_e64 v34, v34, v65, s[24:25]
	v_cndmask_b32_e64 v33, v33, v44, s[28:29]
	v_cndmask_b32_e32 v32, v32, v45, vcc
	v_cndmask_b32_e64 v44, v34, v35, s[4:5]
	v_cndmask_b32_e64 v44, v44, v32, s[2:3]
	v_cndmask_b32_e64 v44, v44, v33, s[0:1]
	v_mul_f32_e32 v45, v48, v44
	v_mul_f32_e32 v48, v50, v44
	v_mul_f32_e32 v50, v52, v44
	v_mul_f32_e32 v52, v54, v44
	v_mul_f32_e32 v54, v56, v44
	v_mul_f32_e32 v56, v58, v44
	v_mul_f32_e32 v58, v60, v44
	v_mul_f32_e32 v44, v62, v44
	v_add_co_u32_e32 v30, vcc, s39, v30
	v_mul_f32_e32 v0, v200, v45
	v_mul_f32_e32 v1, v201, v48
	v_mul_f32_e32 v2, v202, v50
	v_mul_f32_e32 v3, v203, v52
	v_mul_f32_e32 v4, v204, v54
	v_mul_f32_e32 v5, v205, v56
	v_mul_f32_e32 v6, v206, v58
	v_mul_f32_e32 v7, v207, v44
	v_cvt_pk_bf16_f32 v0, v0, v1
	v_cvt_pk_bf16_f32 v1, v2, v3
	v_cvt_pk_bf16_f32 v2, v4, v5
	v_cvt_pk_bf16_f32 v3, v6, v7
	global_store_dwordx4 v[46:47], v[0:3], off offset:1024
	v_cndmask_b32_e64 v44, v34, v35, s[10:11]
	v_cndmask_b32_e64 v44, v44, v32, s[8:9]
	v_cndmask_b32_e64 v44, v44, v33, s[6:7]
	v_mul_f32_e32 v45, v49, v44
	v_mul_f32_e32 v46, v51, v44
	v_mul_f32_e32 v47, v53, v44
	v_mul_f32_e32 v48, v55, v44
	v_addc_co_u32_e32 v31, vcc, 0, v31, vcc
	v_mul_f32_e32 v49, v57, v44
	v_mul_f32_e32 v50, v59, v44
	v_mul_f32_e32 v51, v61, v44
	v_mul_f32_e32 v44, v63, v44
	v_add_co_u32_e32 v28, vcc, 0xee95000, v28
	v_mul_f32_e32 v0, v208, v45
	v_mul_f32_e32 v1, v209, v46
	v_mul_f32_e32 v2, v210, v47
	v_mul_f32_e32 v3, v211, v48
	v_mul_f32_e32 v4, v212, v49
	v_mul_f32_e32 v5, v213, v50
	v_mul_f32_e32 v6, v214, v51
	v_mul_f32_e32 v7, v215, v44
	v_cvt_pk_bf16_f32 v0, v0, v1
	v_cvt_pk_bf16_f32 v1, v2, v3
	v_cvt_pk_bf16_f32 v2, v4, v5
	v_cvt_pk_bf16_f32 v3, v6, v7
	global_store_dwordx4 v[30:31], v[0:3], off offset:1024
	v_cndmask_b32_e64 v30, v34, v35, s[20:21]
	v_cndmask_b32_e64 v30, v30, v32, s[18:19]
	v_cndmask_b32_e64 v30, v30, v33, s[16:17]
	v_mul_f32_e32 v31, v42, v30
	v_mul_f32_e32 v32, v43, v30
	v_mul_f32_e32 v33, v41, v30
	v_mul_f32_e32 v34, v40, v30
	v_addc_co_u32_e32 v29, vcc, 0, v29, vcc
	v_mul_f32_e32 v35, v39, v30
	v_mul_f32_e32 v38, v38, v30
	v_mul_f32_e32 v37, v37, v30
	v_mul_f32_e32 v30, v36, v30
	v_mul_f32_e32 v0, v31, v216
	v_mul_f32_e32 v1, v32, v217
	v_mul_f32_e32 v2, v33, v218
	v_mul_f32_e32 v3, v34, v219
	v_mul_f32_e32 v4, v35, v220
	v_mul_f32_e32 v5, v38, v221
	v_mul_f32_e32 v6, v37, v222
	v_mul_f32_e32 v7, v30, v223
	v_cvt_pk_bf16_f32 v0, v0, v1
	v_cvt_pk_bf16_f32 v1, v2, v3
	v_cvt_pk_bf16_f32 v2, v4, v5
	v_cvt_pk_bf16_f32 v3, v6, v7
	global_store_dwordx4 v[28:29], v[0:3], off offset:1024
	s_cbranch_scc1 .LBB0_1543

.LBB0_1713:
	global_load_dwordx4 v[164:167], v[4:5], off
	global_load_dwordx4 v[168:171], v[4:5], off offset:1024
	global_load_dwordx4 v[172:175], v[4:5], off offset:2048
	global_load_dwordx4 v[176:179], v[4:5], off offset:3072
	v_lshl_add_u64 v[6:7], s[8:9], 0, v[2:3]
	v_add_co_u32_e64 v30, s[0:1], s10, v6
	v_lshl_add_u64 v[8:9], s[2:3], 0, v[2:3]
	s_nop 0
	v_addc_co_u32_e64 v31, s[0:1], 0, v7, s[0:1]
	v_add_co_u32_e32 v158, vcc, 0x4000000, v8
	v_add_co_u32_e64 v46, s[0:1], s11, v6
	s_nop 0
	v_addc_co_u32_e32 v159, vcc, 0, v9, vcc
	v_addc_co_u32_e64 v47, s[0:1], 0, v7, s[0:1]
	v_add_co_u32_e64 v62, s[0:1], s12, v6
	v_add_co_u32_e32 v8, vcc, 0x14114000, v6
	s_nop 0
	v_addc_co_u32_e64 v63, s[0:1], 0, v7, s[0:1]
	v_addc_co_u32_e32 v9, vcc, 0, v7, vcc
	v_add_co_u32_e64 v78, s[0:1], s13, v6
	v_add_co_u32_e32 v126, vcc, 0x14314000, v6
	s_nop 0
	v_addc_co_u32_e64 v79, s[0:1], 0, v7, s[0:1]
	v_addc_co_u32_e32 v127, vcc, 0, v7, vcc
	global_load_dwordx4 v[18:21], v[30:31], off
	global_load_dwordx4 v[22:25], v[30:31], off offset:1024
	global_load_dwordx4 v[26:29], v[30:31], off offset:2048
	s_nop 0
	global_load_dwordx4 v[30:33], v[30:31], off offset:3072
	s_nop 0
	global_load_dwordx4 v[34:37], v[46:47], off
	global_load_dwordx4 v[38:41], v[46:47], off offset:1024
	global_load_dwordx4 v[42:45], v[46:47], off offset:2048
	s_nop 0
	global_load_dwordx4 v[46:49], v[46:47], off offset:3072
	s_nop 0
	global_load_dwordx4 v[50:53], v[62:63], off
	global_load_dwordx4 v[54:57], v[62:63], off offset:1024
	global_load_dwordx4 v[58:61], v[62:63], off offset:2048
	s_nop 0
	global_load_dwordx4 v[62:65], v[62:63], off offset:3072
	s_nop 0
	global_load_dwordx4 v[66:69], v[78:79], off
	global_load_dwordx4 v[70:73], v[78:79], off offset:1024
	global_load_dwordx4 v[74:77], v[78:79], off offset:2048
	s_nop 0
	global_load_dwordx4 v[78:81], v[78:79], off offset:3072
	s_nop 0
	global_load_dwordx4 v[82:85], v[158:159], off
	global_load_dwordx4 v[86:89], v[158:159], off offset:1024
	global_load_dwordx4 v[90:93], v[158:159], off offset:2048
	global_load_dwordx4 v[94:97], v[158:159], off offset:3072
	global_load_dwordx4 v[98:101], v[8:9], off
	global_load_dwordx4 v[102:105], v[8:9], off offset:1024
	global_load_dwordx4 v[106:109], v[8:9], off offset:2048
	global_load_dwordx4 v[110:113], v[8:9], off offset:3072
	v_add_co_u32_e32 v8, vcc, 0x14514000, v6
	global_load_dwordx4 v[114:117], v[126:127], off
	global_load_dwordx4 v[118:121], v[126:127], off offset:1024
	global_load_dwordx4 v[122:125], v[126:127], off offset:2048
	s_nop 0
	global_load_dwordx4 v[126:129], v[126:127], off offset:3072
	v_addc_co_u32_e32 v9, vcc, 0, v7, vcc
	v_add_co_u32_e32 v154, vcc, 0x14714000, v6
	global_load_dwordx4 v[130:133], v[8:9], off
	global_load_dwordx4 v[134:137], v[8:9], off offset:1024
	global_load_dwordx4 v[138:141], v[8:9], off offset:2048
	global_load_dwordx4 v[142:145], v[8:9], off offset:3072
	v_addc_co_u32_e32 v155, vcc, 0, v7, vcc
	global_load_dwordx4 v[6:9], v[154:155], off
	global_load_dwordx4 v[146:149], v[154:155], off offset:1024
	global_load_dwordx4 v[150:153], v[154:155], off offset:2048
	s_nop 0
	global_load_dwordx4 v[154:157], v[154:155], off offset:3072
	s_add_i32 s16, s15, 0x4000
	s_ashr_i32 s17, s16, 31
	s_lshl_b64 s[0:1], s[16:17], 11
	v_lshl_add_u64 v[160:161], v[0:1], 0, s[0:1]
	s_add_i32 s15, s15, s92
	s_add_u32 s2, s2, s4
	s_addc_u32 s3, s3, s5
	s_add_u32 s8, s8, s4
	s_addc_u32 s9, s9, s5
	s_cmpk_lt_i32 s15, 0x200
	s_waitcnt vmcnt(0)
	v_pk_add_f32 v[84:85], v[84:85], v[100:101]
	v_pk_add_f32 v[82:83], v[82:83], v[98:99]
	v_pk_add_f32 v[88:89], v[88:89], v[104:105]
	v_pk_add_f32 v[86:87], v[86:87], v[102:103]
	v_pk_add_f32 v[92:93], v[92:93], v[108:109]
	v_pk_add_f32 v[90:91], v[90:91], v[106:107]
	v_pk_add_f32 v[96:97], v[96:97], v[112:113]
	v_pk_add_f32 v[94:95], v[94:95], v[110:111]
	v_pk_add_f32 v[84:85], v[84:85], v[116:117]
	v_pk_add_f32 v[82:83], v[82:83], v[114:115]
	v_pk_add_f32 v[88:89], v[88:89], v[120:121]
	v_pk_add_f32 v[86:87], v[86:87], v[118:119]
	v_pk_add_f32 v[92:93], v[92:93], v[124:125]
	v_pk_add_f32 v[90:91], v[90:91], v[122:123]
	v_pk_add_f32 v[96:97], v[96:97], v[128:129]
	v_pk_add_f32 v[94:95], v[94:95], v[126:127]
	v_pk_add_f32 v[84:85], v[84:85], v[132:133]
	v_pk_add_f32 v[82:83], v[82:83], v[130:131]
	v_pk_add_f32 v[88:89], v[88:89], v[136:137]
	v_pk_add_f32 v[86:87], v[86:87], v[134:135]
	v_pk_add_f32 v[92:93], v[92:93], v[140:141]
	v_pk_add_f32 v[90:91], v[90:91], v[138:139]
	v_pk_add_f32 v[96:97], v[96:97], v[144:145]
	v_pk_add_f32 v[94:95], v[94:95], v[142:143]
	v_pk_add_f32 v[8:9], v[84:85], v[8:9]
	v_pk_add_f32 v[6:7], v[82:83], v[6:7]
	v_pk_add_f32 v[82:83], v[88:89], v[148:149]
	v_pk_add_f32 v[84:85], v[86:87], v[146:147]
	v_pk_add_f32 v[86:87], v[92:93], v[152:153]
	v_pk_add_f32 v[88:89], v[90:91], v[150:151]
	v_pk_add_f32 v[90:91], v[96:97], v[156:157]
	v_pk_add_f32 v[92:93], v[94:95], v[154:155]
	v_pk_add_f32 v[8:9], v[8:9], v[20:21]
	v_pk_add_f32 v[6:7], v[6:7], v[18:19]
	v_pk_add_f32 v[18:19], v[82:83], v[24:25]
	v_pk_add_f32 v[20:21], v[84:85], v[22:23]
	v_pk_add_f32 v[22:23], v[86:87], v[28:29]
	v_pk_add_f32 v[24:25], v[88:89], v[26:27]
	v_pk_add_f32 v[26:27], v[90:91], v[32:33]
	v_pk_add_f32 v[28:29], v[92:93], v[30:31]
	v_pk_add_f32 v[8:9], v[8:9], v[36:37]
	v_pk_add_f32 v[6:7], v[6:7], v[34:35]
	v_pk_add_f32 v[18:19], v[18:19], v[40:41]
	v_pk_add_f32 v[20:21], v[20:21], v[38:39]
	v_pk_add_f32 v[22:23], v[22:23], v[44:45]
	v_pk_add_f32 v[24:25], v[24:25], v[42:43]
	v_pk_add_f32 v[26:27], v[26:27], v[48:49]
	v_pk_add_f32 v[28:29], v[28:29], v[46:47]
	v_pk_add_f32 v[8:9], v[8:9], v[52:53]
	v_pk_add_f32 v[6:7], v[6:7], v[50:51]
	v_pk_add_f32 v[18:19], v[18:19], v[56:57]
	v_pk_add_f32 v[30:31], v[20:21], v[54:55]
	v_pk_add_f32 v[22:23], v[22:23], v[60:61]
	v_pk_add_f32 v[32:33], v[24:25], v[58:59]
	v_pk_add_f32 v[26:27], v[26:27], v[64:65]
	v_pk_add_f32 v[34:35], v[28:29], v[62:63]
	v_pk_add_f32 v[8:9], v[8:9], v[68:69]
	v_pk_add_f32 v[6:7], v[6:7], v[66:67]
	v_pk_add_f32 v[20:21], v[18:19], v[72:73]
	v_pk_add_f32 v[18:19], v[30:31], v[70:71]
	v_pk_add_f32 v[24:25], v[22:23], v[76:77]
	v_pk_add_f32 v[22:23], v[32:33], v[74:75]
	v_pk_add_f32 v[28:29], v[26:27], v[80:81]
	v_pk_add_f32 v[26:27], v[34:35], v[78:79]
	global_store_dwordx4 v[158:159], v[6:9], off
	global_store_dwordx4 v[158:159], v[18:21], off offset:1024
	global_store_dwordx4 v[158:159], v[22:25], off offset:2048
	global_store_dwordx4 v[158:159], v[26:29], off offset:3072
	v_pk_mul_f32 v[34:35], v[8:9], v[8:9]
	v_pk_mul_f32 v[36:37], v[6:7], v[6:7]
	v_pk_mul_f32 v[38:39], v[20:21], v[20:21]
	v_pk_mul_f32 v[40:41], v[18:19], v[18:19]
	v_pk_mov_b32 v[46:47], v[36:37], v[34:35] op_sel:[1,0]
	v_mov_b32_e32 v37, v35
	v_pk_mov_b32 v[34:35], v[40:41], v[38:39] op_sel:[1,0]
	v_mov_b32_e32 v41, v39
	v_mul_f32_e32 v45, v27, v27
	v_mul_f32_e32 v42, v23, v23
	v_mul_f32_e32 v44, v25, v25
	v_pk_add_f32 v[36:37], v[46:47], v[36:37]
	v_pk_add_f32 v[34:35], v[34:35], v[40:41]
	v_mul_f32_e32 v17, v26, v26
	v_mul_f32_e32 v48, v28, v28
	v_mul_f32_e32 v49, v29, v29
	v_pk_fma_f32 v[38:39], v[22:23], v[22:23], v[42:43] op_sel_hi:[1,1,0]
	v_pk_fma_f32 v[42:43], v[24:25], v[24:25], v[44:45] op_sel_hi:[1,1,0]
	v_pk_add_f32 v[36:37], v[36:37], v[36:37] op_sel:[0,1] op_sel_hi:[1,0]
	v_pk_add_f32 v[34:35], v[34:35], v[34:35] op_sel:[0,1] op_sel_hi:[1,0]
	v_mov_b32_e32 v39, v48
	v_mov_b32_e32 v43, v49
	v_mov_b32_e32 v37, v17
	v_mov_b32_e32 v35, v45
	v_pk_add_f32 v[38:39], v[38:39], v[42:43]
	v_pk_add_f32 v[34:35], v[36:37], v[34:35]
	s_nop 0
	v_pk_add_f32 v[34:35], v[34:35], v[38:39]
	s_nop 0
	v_add_f32_e32 v17, v34, v35
	ds_bpermute_b32 v34, v10, v17
	s_waitcnt lgkmcnt(0)
	v_add_f32_e32 v17, v17, v34
	ds_bpermute_b32 v34, v11, v17
	s_waitcnt lgkmcnt(0)
	v_add_f32_e32 v17, v17, v34
	ds_bpermute_b32 v34, v12, v17
	s_waitcnt lgkmcnt(0)
	v_add_f32_e32 v17, v17, v34
	ds_bpermute_b32 v34, v13, v17
	s_waitcnt lgkmcnt(0)
	v_add_f32_e32 v17, v17, v34
	ds_bpermute_b32 v34, v14, v17
	s_waitcnt lgkmcnt(0)
	v_add_f32_e32 v17, v17, v34
	ds_bpermute_b32 v34, v15, v17
	s_waitcnt lgkmcnt(0)
	v_add_f32_e32 v17, v17, v34
	v_fmamk_f32 v17, v17, 0x3a800000, v16
	v_mul_f32_e32 v34, 0x4b800000, v17
	v_cmp_gt_f32_e32 vcc, s14, v17
	s_nop 1
	v_cndmask_b32_e32 v17, v17, v34, vcc
	v_rsq_f32_e32 v17, v17
	s_nop 0
	v_mul_f32_e32 v34, 0x45800000, v17
	v_cndmask_b32_e32 v17, v17, v34, vcc
	v_mul_f32_e32 v6, v6, v17
	v_mul_f32_e32 v7, v7, v17
	v_mul_f32_e32 v8, v8, v17
	v_mul_f32_e32 v9, v9, v17
	v_mul_f32_e32 v6, v164, v6
	v_mul_f32_e32 v7, v165, v7
	v_mul_f32_e32 v8, v166, v8
	v_mul_f32_e32 v9, v167, v9
	v_cvt_pk_bf16_f32 v6, v6, v7
	v_cvt_pk_bf16_f32 v7, v8, v9
	global_store_dwordx2 v[160:161], v[6:7], off
	v_mul_f32_e32 v18, v18, v17
	v_mul_f32_e32 v19, v19, v17
	v_mul_f32_e32 v20, v20, v17
	v_mul_f32_e32 v21, v21, v17
	v_mul_f32_e32 v6, v168, v18
	v_mul_f32_e32 v7, v169, v19
	v_mul_f32_e32 v8, v170, v20
	v_mul_f32_e32 v9, v171, v21
	v_cvt_pk_bf16_f32 v6, v6, v7
	v_cvt_pk_bf16_f32 v7, v8, v9
	global_store_dwordx2 v[160:161], v[6:7], off offset:512
	v_mul_f32_e32 v18, v22, v17
	v_mul_f32_e32 v19, v23, v17
	v_mul_f32_e32 v20, v24, v17
	v_mul_f32_e32 v21, v25, v17
	v_mul_f32_e32 v6, v18, v172
	v_mul_f32_e32 v7, v19, v173
	v_mul_f32_e32 v8, v20, v174
	v_mul_f32_e32 v9, v21, v175
	v_cvt_pk_bf16_f32 v6, v6, v7
	v_cvt_pk_bf16_f32 v7, v8, v9
	global_store_dwordx2 v[160:161], v[6:7], off offset:1024
	v_mul_f32_e32 v18, v26, v17
	v_mul_f32_e32 v19, v27, v17
	v_mul_f32_e32 v20, v28, v17
	v_mul_f32_e32 v17, v29, v17
	v_mul_f32_e32 v6, v18, v176
	v_mul_f32_e32 v7, v19, v177
	v_mul_f32_e32 v8, v20, v178
	v_mul_f32_e32 v9, v17, v179
	v_cvt_pk_bf16_f32 v6, v6, v7
	v_cvt_pk_bf16_f32 v7, v8, v9
	global_store_dwordx2 v[160:161], v[6:7], off offset:1536
	s_cbranch_scc1 .LBB0_1713

.LBB0_1955:
	s_nop 0
	v_lshl_add_u64 v[6:7], s[6:7], 0, v[0:1]
	v_add_co_u32_e64 v82, s[0:1], s8, v6
	v_lshl_add_u64 v[8:9], s[2:3], 0, v[0:1]
	s_nop 0
	v_addc_co_u32_e64 v83, s[0:1], 0, v7, s[0:1]
	v_add_co_u32_e64 v84, s[0:1], s9, v6
	v_add_co_u32_e32 v8, vcc, 0x4000000, v8
	s_nop 0
	v_addc_co_u32_e64 v85, s[0:1], 0, v7, s[0:1]
	v_add_co_u32_e64 v86, s[0:1], s10, v6
	v_addc_co_u32_e32 v9, vcc, 0, v9, vcc
	s_nop 0
	v_addc_co_u32_e64 v87, s[0:1], 0, v7, s[0:1]
	v_add_co_u32_e64 v118, s[0:1], s11, v6
	v_add_co_u32_e32 v162, vcc, 0x14114000, v6
	s_nop 0
	v_addc_co_u32_e64 v119, s[0:1], 0, v7, s[0:1]
	v_add_co_u32_e64 v120, s[0:1], s12, v6
	v_addc_co_u32_e32 v163, vcc, 0, v7, vcc
	s_nop 0
	v_addc_co_u32_e64 v121, s[0:1], 0, v7, s[0:1]
	v_add_co_u32_e64 v122, s[0:1], s13, v6
	global_load_dwordx4 v[18:21], v[2:3], off
	global_load_dwordx4 v[212:215], v[2:3], off offset:1024
	global_load_dwordx4 v[216:219], v[2:3], off offset:2048
	global_load_dwordx4 v[220:223], v[2:3], off offset:3072
	s_nop 0
	v_addc_co_u32_e64 v123, s[0:1], 0, v7, s[0:1]
	v_add_co_u32_e64 v130, s[0:1], s14, v6
	s_add_i32 s16, s18, 0x4000
	s_nop 0
	v_addc_co_u32_e64 v131, s[0:1], 0, v7, s[0:1]
	global_load_dwordx4 v[22:25], v[82:83], off
	global_load_dwordx4 v[26:29], v[82:83], off offset:1024
	global_load_dwordx4 v[30:33], v[82:83], off offset:2048
	global_load_dwordx4 v[34:37], v[82:83], off offset:3072
	global_load_dwordx4 v[38:41], v[84:85], off
	global_load_dwordx4 v[42:45], v[84:85], off offset:1024
	global_load_dwordx4 v[46:49], v[84:85], off offset:2048
	global_load_dwordx4 v[50:53], v[84:85], off offset:3072
	global_load_dwordx4 v[54:57], v[86:87], off
	global_load_dwordx4 v[58:61], v[86:87], off offset:1024
	global_load_dwordx4 v[62:65], v[86:87], off offset:2048
	global_load_dwordx4 v[66:69], v[86:87], off offset:3072
	global_load_dwordx4 v[70:73], v[118:119], off
	global_load_dwordx4 v[74:77], v[118:119], off offset:1024
	global_load_dwordx4 v[78:81], v[118:119], off offset:2048
	global_load_dwordx4 v[82:85], v[118:119], off offset:3072
	s_nop 0
	global_load_dwordx4 v[86:89], v[120:121], off
	global_load_dwordx4 v[90:93], v[120:121], off offset:1024
	global_load_dwordx4 v[94:97], v[120:121], off offset:2048
	global_load_dwordx4 v[98:101], v[120:121], off offset:3072
	global_load_dwordx4 v[102:105], v[122:123], off
	global_load_dwordx4 v[106:109], v[122:123], off offset:1024
	global_load_dwordx4 v[110:113], v[122:123], off offset:2048
	global_load_dwordx4 v[114:117], v[122:123], off offset:3072
	s_nop 0
	global_load_dwordx4 v[118:121], v[130:131], off
	global_load_dwordx4 v[122:125], v[130:131], off offset:1024
	global_load_dwordx4 v[126:129], v[130:131], off offset:2048
	s_nop 0
	global_load_dwordx4 v[130:133], v[130:131], off offset:3072
	s_nop 0
	global_load_dwordx4 v[134:137], v[8:9], off
	global_load_dwordx4 v[138:141], v[8:9], off offset:1024
	global_load_dwordx4 v[142:145], v[8:9], off offset:2048
	global_load_dwordx4 v[146:149], v[8:9], off offset:3072
	v_add_co_u32_e32 v8, vcc, 0x14314000, v6
	global_load_dwordx4 v[150:153], v[162:163], off
	global_load_dwordx4 v[154:157], v[162:163], off offset:1024
	global_load_dwordx4 v[158:161], v[162:163], off offset:2048
	s_nop 0
	global_load_dwordx4 v[162:165], v[162:163], off offset:3072
	v_addc_co_u32_e32 v9, vcc, 0, v7, vcc
	v_add_co_u32_e32 v194, vcc, 0x14514000, v6
	global_load_dwordx4 v[166:169], v[8:9], off
	global_load_dwordx4 v[170:173], v[8:9], off offset:1024
	global_load_dwordx4 v[174:177], v[8:9], off offset:2048
	global_load_dwordx4 v[178:181], v[8:9], off offset:3072
	v_addc_co_u32_e32 v195, vcc, 0, v7, vcc
	v_add_co_u32_e32 v206, vcc, 0x14714000, v6
	global_load_dwordx4 v[182:185], v[194:195], off
	global_load_dwordx4 v[186:189], v[194:195], off offset:1024
	global_load_dwordx4 v[190:193], v[194:195], off offset:2048
	s_nop 0
	global_load_dwordx4 v[194:197], v[194:195], off offset:3072
	v_addc_co_u32_e32 v207, vcc, 0, v7, vcc
	global_load_dwordx4 v[6:9], v[206:207], off
	global_load_dwordx4 v[198:201], v[206:207], off offset:1024
	global_load_dwordx4 v[202:205], v[206:207], off offset:2048
	s_nop 0
	global_load_dwordx4 v[206:209], v[206:207], off offset:3072
	s_ashr_i32 s17, s16, 31
	s_lshl_b64 s[0:1], s[16:17], 12
	v_lshl_add_u64 v[210:211], v[4:5], 0, s[0:1]
	s_add_i32 s18, s18, s92
	s_add_u32 s2, s2, s4
	s_addc_u32 s3, s3, s5
	s_add_u32 s6, s6, s4
	s_addc_u32 s7, s7, s5
	s_cmpk_gt_i32 s18, 0x1ff
	s_waitcnt vmcnt(0)
	v_pk_add_f32 v[136:137], v[136:137], v[152:153]
	v_pk_add_f32 v[134:135], v[134:135], v[150:151]
	v_pk_add_f32 v[140:141], v[140:141], v[156:157]
	v_pk_add_f32 v[138:139], v[138:139], v[154:155]
	v_pk_add_f32 v[144:145], v[144:145], v[160:161]
	v_pk_add_f32 v[136:137], v[136:137], v[168:169]
	v_pk_add_f32 v[134:135], v[134:135], v[166:167]
	v_pk_add_f32 v[140:141], v[140:141], v[172:173]
	v_pk_add_f32 v[138:139], v[138:139], v[170:171]
	v_pk_add_f32 v[142:143], v[142:143], v[158:159]
	v_pk_add_f32 v[146:147], v[146:147], v[162:163]
	v_pk_add_f32 v[136:137], v[136:137], v[184:185]
	v_pk_add_f32 v[134:135], v[134:135], v[182:183]
	v_pk_add_f32 v[140:141], v[140:141], v[188:189]
	v_pk_add_f32 v[138:139], v[138:139], v[186:187]
	v_pk_add_f32 v[148:149], v[148:149], v[164:165]
	v_pk_add_f32 v[144:145], v[144:145], v[176:177]
	v_pk_add_f32 v[142:143], v[142:143], v[174:175]
	v_pk_add_f32 v[146:147], v[146:147], v[178:179]
	v_pk_add_f32 v[8:9], v[136:137], v[8:9]
	v_pk_add_f32 v[6:7], v[134:135], v[6:7]
	v_pk_add_f32 v[134:135], v[140:141], v[200:201]
	v_pk_add_f32 v[136:137], v[138:139], v[198:199]
	v_pk_add_f32 v[148:149], v[148:149], v[180:181]
	v_pk_add_f32 v[144:145], v[144:145], v[192:193]
	v_pk_add_f32 v[142:143], v[142:143], v[190:191]
	v_pk_add_f32 v[146:147], v[146:147], v[194:195]
	v_pk_add_f32 v[8:9], v[8:9], v[24:25]
	v_pk_add_f32 v[6:7], v[6:7], v[22:23]
	v_pk_add_f32 v[22:23], v[134:135], v[28:29]
	v_pk_add_f32 v[24:25], v[136:137], v[26:27]
	v_pk_add_f32 v[148:149], v[148:149], v[196:197]
	v_pk_add_f32 v[138:139], v[144:145], v[204:205]
	v_pk_add_f32 v[140:141], v[142:143], v[202:203]
	v_pk_add_f32 v[144:145], v[146:147], v[206:207]
	v_pk_add_f32 v[8:9], v[8:9], v[40:41]
	v_pk_add_f32 v[6:7], v[6:7], v[38:39]
	v_pk_add_f32 v[22:23], v[22:23], v[44:45]
	v_pk_add_f32 v[24:25], v[24:25], v[42:43]
	v_pk_add_f32 v[142:143], v[148:149], v[208:209]
	v_pk_add_f32 v[26:27], v[138:139], v[32:33]
	v_pk_add_f32 v[28:29], v[140:141], v[30:31]
	v_pk_add_f32 v[32:33], v[144:145], v[34:35]
	v_pk_add_f32 v[8:9], v[8:9], v[56:57]
	v_pk_add_f32 v[6:7], v[6:7], v[54:55]
	v_pk_add_f32 v[22:23], v[22:23], v[60:61]
	v_pk_add_f32 v[24:25], v[24:25], v[58:59]
	v_pk_add_f32 v[30:31], v[142:143], v[36:37]
	v_pk_add_f32 v[26:27], v[26:27], v[48:49]
	v_pk_add_f32 v[28:29], v[28:29], v[46:47]
	v_pk_add_f32 v[32:33], v[32:33], v[50:51]
	v_pk_add_f32 v[8:9], v[8:9], v[72:73]
	v_pk_add_f32 v[6:7], v[6:7], v[70:71]
	v_pk_add_f32 v[22:23], v[22:23], v[76:77]
	v_pk_add_f32 v[24:25], v[24:25], v[74:75]
	v_pk_add_f32 v[30:31], v[30:31], v[52:53]
	v_pk_add_f32 v[26:27], v[26:27], v[64:65]
	v_pk_add_f32 v[28:29], v[28:29], v[62:63]
	v_pk_add_f32 v[32:33], v[32:33], v[66:67]
	v_pk_add_f32 v[8:9], v[8:9], v[88:89]
	v_pk_add_f32 v[6:7], v[6:7], v[86:87]
	v_pk_add_f32 v[22:23], v[22:23], v[92:93]
	v_pk_add_f32 v[24:25], v[24:25], v[90:91]
	v_pk_add_f32 v[30:31], v[30:31], v[68:69]
	v_pk_add_f32 v[26:27], v[26:27], v[80:81]
	v_pk_add_f32 v[28:29], v[28:29], v[78:79]
	v_pk_add_f32 v[32:33], v[32:33], v[82:83]
	v_pk_add_f32 v[8:9], v[8:9], v[104:105]
	v_pk_add_f32 v[6:7], v[6:7], v[102:103]
	v_pk_add_f32 v[22:23], v[22:23], v[108:109]
	v_pk_add_f32 v[24:25], v[24:25], v[106:107]
	v_pk_add_f32 v[30:31], v[30:31], v[84:85]
	v_pk_add_f32 v[26:27], v[26:27], v[96:97]
	v_pk_add_f32 v[28:29], v[28:29], v[94:95]
	v_pk_add_f32 v[32:33], v[32:33], v[98:99]
	v_pk_add_f32 v[8:9], v[8:9], v[120:121]
	v_pk_add_f32 v[6:7], v[6:7], v[118:119]
	v_pk_add_f32 v[22:23], v[22:23], v[124:125]
	v_pk_add_f32 v[24:25], v[24:25], v[122:123]
	v_pk_add_f32 v[30:31], v[30:31], v[100:101]
	v_pk_add_f32 v[26:27], v[26:27], v[112:113]
	v_pk_add_f32 v[28:29], v[28:29], v[110:111]
	v_pk_add_f32 v[32:33], v[32:33], v[114:115]
	v_pk_fma_f32 v[8:9], v[120:121], 0, v[8:9] op_sel_hi:[1,0,1]
	v_pk_fma_f32 v[6:7], v[118:119], 0, v[6:7] op_sel_hi:[1,0,1]
	v_pk_fma_f32 v[22:23], v[124:125], 0, v[22:23] op_sel_hi:[1,0,1]
	v_pk_fma_f32 v[24:25], v[122:123], 0, v[24:25] op_sel_hi:[1,0,1]
	v_pk_add_f32 v[30:31], v[30:31], v[116:117]
	v_pk_add_f32 v[26:27], v[26:27], v[128:129]
	v_pk_add_f32 v[28:29], v[28:29], v[126:127]
	v_pk_add_f32 v[32:33], v[32:33], v[130:131]
	v_pk_mul_f32 v[34:35], v[8:9], v[8:9]
	v_pk_mul_f32 v[36:37], v[6:7], v[6:7]
	v_pk_mul_f32 v[38:39], v[22:23], v[22:23]
	v_pk_mul_f32 v[40:41], v[24:25], v[24:25]
	v_pk_add_f32 v[30:31], v[30:31], v[132:133]
	v_pk_fma_f32 v[26:27], v[128:129], 0, v[26:27] op_sel_hi:[1,0,1]
	v_pk_fma_f32 v[28:29], v[126:127], 0, v[28:29] op_sel_hi:[1,0,1]
	v_pk_fma_f32 v[32:33], v[130:131], 0, v[32:33] op_sel_hi:[1,0,1]
	v_pk_mov_b32 v[46:47], v[36:37], v[34:35] op_sel:[1,0]
	v_mov_b32_e32 v37, v35
	v_pk_mov_b32 v[34:35], v[40:41], v[38:39] op_sel:[1,0]
	v_mov_b32_e32 v41, v39
	v_pk_fma_f32 v[30:31], v[132:133], 0, v[30:31] op_sel_hi:[1,0,1]
	v_mul_f32_e32 v45, v33, v33
	v_mul_f32_e32 v42, v29, v29
	v_mul_f32_e32 v44, v27, v27
	v_pk_add_f32 v[36:37], v[46:47], v[36:37]
	v_pk_add_f32 v[34:35], v[34:35], v[40:41]
	v_mul_f32_e32 v17, v32, v32
	v_mul_f32_e32 v48, v30, v30
	v_mul_f32_e32 v49, v31, v31
	v_pk_fma_f32 v[38:39], v[28:29], v[28:29], v[42:43] op_sel_hi:[1,1,0]
	v_pk_fma_f32 v[42:43], v[26:27], v[26:27], v[44:45] op_sel_hi:[1,1,0]
	v_pk_add_f32 v[36:37], v[36:37], v[36:37] op_sel:[0,1] op_sel_hi:[1,0]
	v_pk_add_f32 v[34:35], v[34:35], v[34:35] op_sel:[0,1] op_sel_hi:[1,0]
	v_mov_b32_e32 v39, v48
	v_mov_b32_e32 v43, v49
	v_mov_b32_e32 v37, v17
	v_mov_b32_e32 v35, v45
	v_pk_add_f32 v[38:39], v[38:39], v[42:43]
	v_pk_add_f32 v[34:35], v[36:37], v[34:35]
	s_nop 0
	v_pk_add_f32 v[34:35], v[34:35], v[38:39]
	s_nop 0
	v_add_f32_e32 v17, v34, v35
	ds_bpermute_b32 v34, v10, v17
	s_waitcnt lgkmcnt(0)
	v_add_f32_e32 v17, v17, v34
	ds_bpermute_b32 v34, v11, v17
	s_waitcnt lgkmcnt(0)
	v_add_f32_e32 v17, v17, v34
	ds_bpermute_b32 v34, v12, v17
	s_waitcnt lgkmcnt(0)
	v_add_f32_e32 v17, v17, v34
	ds_bpermute_b32 v34, v13, v17
	s_waitcnt lgkmcnt(0)
	v_add_f32_e32 v17, v17, v34
	ds_bpermute_b32 v34, v14, v17
	s_waitcnt lgkmcnt(0)
	v_add_f32_e32 v17, v17, v34
	ds_bpermute_b32 v34, v15, v17
	s_waitcnt lgkmcnt(0)
	v_add_f32_e32 v17, v17, v34
	v_fmamk_f32 v17, v17, 0x3a800000, v16
	v_mul_f32_e32 v34, 0x4b800000, v17
	v_cmp_gt_f32_e32 vcc, s15, v17
	s_nop 1
	v_cndmask_b32_e32 v17, v17, v34, vcc
	v_rsq_f32_e32 v17, v17
	s_nop 0
	v_mul_f32_e32 v34, 0x45800000, v17
	v_cndmask_b32_e32 v34, v17, v34, vcc
	v_pk_mul_f32 v[6:7], v[34:35], v[6:7] op_sel_hi:[0,1]
	v_pk_mul_f32 v[8:9], v[34:35], v[8:9] op_sel_hi:[0,1]
	v_pk_mul_f32 v[8:9], v[8:9], v[20:21]
	v_pk_mul_f32 v[6:7], v[6:7], v[18:19]
	global_store_dwordx4 v[210:211], v[6:9], off
	v_pk_mul_f32 v[18:19], v[34:35], v[22:23] op_sel_hi:[0,1]
	v_pk_mul_f32 v[20:21], v[34:35], v[24:25] op_sel_hi:[0,1]
	v_pk_mul_f32 v[6:7], v[20:21], v[212:213]
	v_pk_mul_f32 v[8:9], v[18:19], v[214:215]
	global_store_dwordx4 v[210:211], v[6:9], off offset:1024
	v_pk_mul_f32 v[18:19], v[34:35], v[26:27] op_sel_hi:[0,1]
	v_pk_mul_f32 v[20:21], v[34:35], v[28:29] op_sel_hi:[0,1]
	v_pk_mul_f32 v[6:7], v[20:21], v[216:217]
	v_pk_mul_f32 v[8:9], v[18:19], v[218:219]
	global_store_dwordx4 v[210:211], v[6:9], off offset:2048
	v_pk_mul_f32 v[18:19], v[34:35], v[30:31] op_sel_hi:[0,1]
	v_pk_mul_f32 v[20:21], v[34:35], v[32:33] op_sel_hi:[0,1]
	v_pk_mul_f32 v[6:7], v[20:21], v[220:221]
	v_pk_mul_f32 v[8:9], v[18:19], v[222:223]
	global_store_dwordx4 v[210:211], v[6:9], off offset:3072
	s_cbranch_scc0 .LBB0_1955
